# nt hint on the LRU pass-1 tile-summary store
# speedup vs baseline: 1.0045x; 1.0045x over previous
; DI f4 mfma16(h8 a, h8 b, f4 c) { return __builtin_amdgcn_mfma_f32_16x16x32_f16(a, b, c, 0, 0, 0); }
; DI float sigmoidf_(float x) { return 1.f / (1.f + __expf(-x)); }
; DI void lru_tile(const Params& P, int l, int b, int tile, int g, char* smem, bool final, const LruK& K) {
;     ...
;     {
;       f4 acc[2][4];
; #pragma unroll
;       for (int gt = 0; gt < 2; gt++)
; #pragma unroll
;         for (int n = 0; n < 4; n++) acc[gt][n] = (f4){0.f, 0.f, 0.f, 0.f};
; #pragma unroll
;       for (int kk = 0; kk < 2; kk++) {
;         int row = wave * 16 + fr;
;         h8 af = *(const h8*)(xr16 + row * 128 + (((kk * 4 + fq) ^ ((row >> 1) & 7)) << 4));
; #pragma unroll
;         for (int gt = 0; gt < 2; gt++)
; #pragma unroll
;           for (int n = 0; n < 4; n++) {
;             int orow = n * 16 + fr;
;             h8 bf = *(const h8*)(Wt + (dir * 2 + gt) * 8192 + orow * 128 + (((kk * 4 + fq) ^ ((orow >> 1) & 7)) << 4));
;             acc[gt][n] = mfma16(af, bf, acc[gt][n]);
;           }
;       }
; #pragma unroll
;       for (int n = 0; n < 4; n++) {
;         const float ba = dir == 0 ? K.ba[0][n] : K.ba[1][n], bx = dir == 0 ? K.bx[0][n] : K.bx[1][n], sp8 = dir == 0 ? K.sp8[0][n] : K.sp8[1][n];
; #pragma unroll
;         for (int j = 0; j < 4; j++) {
;           int tl = wave * 16 + fq * 4 + j, c2 = n * 16 + fr;
;           float xv = (float)*(const half_t*)(xr16 + swz128(tl, c2));
;           float rg = sigmoidf_(acc[0][n][j] + ba), ig = sigmoidf_(acc[1][n][j] + bx);
;           float log_a = rg * sp8;
;           float x2 = 2.f * log_a;
;           float om = -x2 * (1.f + x2 * (0.5f + x2 * (0.16666667f + x2 * (0.041666668f + x2 * (0.008333334f + x2 * 0.0013888889f)))));
;           if (x2 < -0.4f) { float a = __expf(log_a); om = 1.f - a * a; }
;           ab[tl * 64 + c2] = make_float2(log_a, sqrtf(om) * (ig * xv));
;         }
;       }
.LBB0_401:
	v_add_u32_e32 v6, v55, v57
	ds_read_b128 v[6:9], v6 offset:32768
	v_lshl_or_b32 v14, s20, 14, v54
	v_add_u32_e32 v15, v14, v57
	ds_read_b128 v[10:13], v15
	v_add_u32_e32 v14, v14, v58
	s_waitcnt lgkmcnt(0)
	v_mfma_f32_16x16x32_f16 a[0:3], v[6:9], v[10:13], 0
	ds_read_b128 v[10:13], v15 offset:2048
	s_waitcnt lgkmcnt(0)
	v_mfma_f32_16x16x32_f16 a[4:7], v[6:9], v[10:13], 0
	ds_read_b128 v[10:13], v15 offset:4096
	s_waitcnt lgkmcnt(0)
	v_mfma_f32_16x16x32_f16 a[8:11], v[6:9], v[10:13], 0
	ds_read_b128 v[10:13], v15 offset:6144
	s_waitcnt lgkmcnt(0)
	v_mfma_f32_16x16x32_f16 a[12:15], v[6:9], v[10:13], 0
	ds_read_b128 v[10:13], v15 offset:8192
	s_waitcnt lgkmcnt(0)
	v_mfma_f32_16x16x32_f16 a[20:23], v[6:9], v[10:13], 0
	ds_read_b128 v[10:13], v15 offset:10240
	s_waitcnt lgkmcnt(0)
	v_mfma_f32_16x16x32_f16 a[32:35], v[6:9], v[10:13], 0
	ds_read_b128 v[10:13], v15 offset:12288
	s_waitcnt lgkmcnt(0)
	v_mfma_f32_16x16x32_f16 a[36:39], v[6:9], v[10:13], 0
	ds_read_b128 v[10:13], v15 offset:14336
	s_waitcnt lgkmcnt(0)
	v_mfma_f32_16x16x32_f16 a[40:43], v[6:9], v[10:13], 0
	v_add_u32_e32 v6, v55, v58
	ds_read_b128 v[6:9], v6 offset:32768
	ds_read_b128 v[10:13], v14
	s_waitcnt lgkmcnt(0)
	v_mfma_f32_16x16x32_f16 a[24:27], v[6:9], v[10:13], a[0:3]
	ds_read_b128 v[10:13], v14 offset:2048
	s_waitcnt lgkmcnt(0)
	v_mfma_f32_16x16x32_f16 a[16:19], v[6:9], v[10:13], a[4:7]
	ds_read_b128 v[10:13], v14 offset:4096
	s_waitcnt lgkmcnt(0)
	v_mfma_f32_16x16x32_f16 a[8:11], v[6:9], v[10:13], a[8:11]
	ds_read_b128 v[10:13], v14 offset:6144
	s_waitcnt lgkmcnt(0)
	v_mfma_f32_16x16x32_f16 a[0:3], v[6:9], v[10:13], a[12:15]
	ds_read_b128 v[10:13], v14 offset:8192
	s_waitcnt lgkmcnt(0)
	v_mfma_f32_16x16x32_f16 a[28:31], v[6:9], v[10:13], a[20:23]
	ds_read_b128 v[10:13], v14 offset:10240
	s_waitcnt lgkmcnt(0)
	v_mfma_f32_16x16x32_f16 a[20:23], v[6:9], v[10:13], a[32:35]
	ds_read_b128 v[10:13], v14 offset:12288
	s_waitcnt lgkmcnt(0)
	v_mfma_f32_16x16x32_f16 a[12:15], v[6:9], v[10:13], a[36:39]
	ds_read_b128 v[10:13], v14 offset:14336
	v_cndmask_b32_e64 v14, v37, v25, s[2:3]
	s_waitcnt lgkmcnt(0)
	v_mfma_f32_16x16x32_f16 a[4:7], v[6:9], v[10:13], a[40:43]
	v_accvgpr_read_b32 v10, a28
	v_add_f32_e32 v10, v14, v10
	v_mul_f32_e32 v10, 0xbfb8aa3b, v10
	v_exp_f32_e32 v10, v10
	ds_read_u16 v8, v59 offset:32768
	v_cndmask_b32_e64 v7, v36, v24, s[2:3]
	v_accvgpr_read_b32 v9, a24
	v_add_f32_e32 v10, 1.0, v10
	v_div_scale_f32 v11, s[0:1], v10, v10, 1.0
	v_rcp_f32_e32 v12, v11
	s_waitcnt lgkmcnt(0)
	v_cvt_f32_f16_e32 v8, v8
	v_add_f32_e32 v9, v7, v9
	v_mul_f32_e32 v9, 0xbfb8aa3b, v9
	v_fma_f32 v13, -v11, v12, 1.0
	v_fmac_f32_e32 v12, v13, v12
	v_div_scale_f32 v13, vcc, 1.0, v10, 1.0
	v_mul_f32_e32 v15, v13, v12
	v_fma_f32 v16, -v11, v15, v13
	v_fmac_f32_e32 v15, v16, v12
	v_fma_f32 v11, -v11, v15, v13
	v_div_fmas_f32 v11, v11, v12, v15
	v_div_fixup_f32 v10, v11, v10, 1.0
	v_mul_f32_e32 v12, v10, v8
	v_accvgpr_read_b32 v10, a29
	v_add_f32_e32 v10, v14, v10
	v_mul_f32_e32 v10, 0xbfb8aa3b, v10
	v_exp_f32_e32 v10, v10
	v_accvgpr_read_b32 v8, a25
	v_add_f32_e32 v8, v7, v8
	v_mul_f32_e32 v8, 0xbfb8aa3b, v8
	v_add_f32_e32 v10, 1.0, v10
	v_div_scale_f32 v11, s[0:1], v10, v10, 1.0
	v_rcp_f32_e32 v13, v11
	v_exp_f32_e32 v9, v9
	v_exp_f32_e32 v8, v8
	v_cndmask_b32_e64 v6, v38, v26, s[2:3]
	v_fma_f32 v15, -v11, v13, 1.0
	v_fmac_f32_e32 v13, v15, v13
	v_div_scale_f32 v15, vcc, 1.0, v10, 1.0
	v_mul_f32_e32 v16, v15, v13
	v_fma_f32 v17, -v11, v16, v15
	v_fmac_f32_e32 v16, v17, v13
	v_fma_f32 v11, -v11, v16, v15
	v_div_fmas_f32 v11, v11, v13, v16
	v_pk_add_f32 v[8:9], v[8:9], 1.0 op_sel_hi:[1,0]
	v_div_fixup_f32 v15, v11, v10, 1.0
	v_div_scale_f32 v10, s[0:1], v9, v9, 1.0
	v_rcp_f32_e32 v11, v10
	v_mul_f32_e32 v6, 0xc1000000, v6
	v_fma_f32 v13, -v10, v11, 1.0
	v_fmac_f32_e32 v11, v13, v11
	v_div_scale_f32 v13, vcc, 1.0, v9, 1.0
	v_mul_f32_e32 v16, v13, v11
	v_fma_f32 v17, -v10, v16, v13
	v_fmac_f32_e32 v16, v17, v11
	v_fma_f32 v10, -v10, v16, v13
	v_div_fmas_f32 v10, v10, v11, v16
	v_div_fixup_f32 v9, v10, v9, 1.0
	v_div_scale_f32 v10, s[0:1], v8, v8, 1.0
	v_rcp_f32_e32 v11, v10
	s_nop 0
	v_fma_f32 v13, -v10, v11, 1.0
	v_fmac_f32_e32 v11, v13, v11
	v_div_scale_f32 v13, vcc, 1.0, v8, 1.0
	v_mul_f32_e32 v16, v13, v11
	v_fma_f32 v17, -v10, v16, v13
	v_fmac_f32_e32 v16, v17, v11
	v_fma_f32 v10, -v10, v16, v13
	v_div_fmas_f32 v10, v10, v11, v16
	v_div_fixup_f32 v8, v10, v8, 1.0
	v_pk_mul_f32 v[8:9], v[6:7], v[8:9] op_sel_hi:[0,1]
	v_pk_add_f32 v[10:11], v[8:9], v[8:9]
	v_mul_f32_e32 v16, 0x3fb8aa3b, v9
	v_fmamk_f32 v13, v11, 0x3ab60b61, v177
	v_fmaak_f32 v13, v11, v13, 0x3d2aaaab
	v_exp_f32_e32 v16, v16
	v_fmaak_f32 v13, v11, v13, 0x3e2aaaab
	v_fma_f32 v13, v11, v13, 0.5
	v_fma_f32 v13, v11, v13, 1.0
	v_mul_f32_e64 v13, v13, -v11
	v_fma_f32 v16, -v16, v16, 1.0
	v_cmp_gt_f32_e64 s[0:1], s41, v11
	v_cmp_gt_f32_e32 vcc, s41, v10
	s_nop 0
	v_cndmask_b32_e64 v11, v13, v16, s[0:1]
	v_cmp_gt_f32_e64 s[0:1], s47, v11
	v_mul_f32_e32 v13, 0x4f800000, v11
	s_nop 0
	v_cndmask_b32_e64 v11, v11, v13, s[0:1]
	v_sqrt_f32_e32 v13, v11
	s_nop 0
	v_add_u32_e32 v16, -1, v13
	v_fma_f32 v17, -v16, v13, v11
	v_cmp_ge_f32_e64 s[6:7], 0, v17
	v_add_u32_e32 v17, 1, v13
	s_nop 0
	v_cndmask_b32_e64 v16, v13, v16, s[6:7]
	v_fma_f32 v13, -v17, v13, v11
	v_cmp_lt_f32_e64 s[6:7], 0, v13
	s_nop 1
	v_cndmask_b32_e64 v13, v16, v17, s[6:7]
	v_mul_f32_e32 v16, 0x37800000, v13
	v_cndmask_b32_e64 v13, v13, v16, s[0:1]
	v_cmp_class_f32_e64 s[0:1], v11, v178
	s_nop 1
	v_cndmask_b32_e64 v11, v13, v11, s[0:1]
	v_mul_f32_e32 v13, v12, v11
	v_fmamk_f32 v11, v10, 0x3ab60b61, v177
	v_fmaak_f32 v11, v10, v11, 0x3d2aaaab
	v_fmaak_f32 v11, v10, v11, 0x3e2aaaab
	v_fma_f32 v11, v10, v11, 0.5
	v_fma_f32 v11, v10, v11, 1.0
	v_mul_f32_e64 v10, v11, -v10
	v_mul_f32_e32 v11, 0x3fb8aa3b, v8
	v_exp_f32_e32 v11, v11
	v_mov_b32_e32 v12, v9
	ds_write_b64 v60, v[12:13] offset:40960
	ds_read_u16 v9, v61 offset:32768
	v_fma_f32 v11, -v11, v11, 1.0
	v_cndmask_b32_e32 v10, v10, v11, vcc
	v_cmp_gt_f32_e32 vcc, s47, v10
	v_mul_f32_e32 v11, 0x4f800000, v10
	s_waitcnt lgkmcnt(0)
; DI float sigmoidf_(float x) { return 1.f / (1.f + __expf(-x)); }
; DI void lru_tile(const Params& P, int l, int b, int tile, int g, char* smem, bool final, const LruK& K) {
;     ...
; #pragma unroll
;       for (int n = 0; n < 4; n++) {
;         const float ba = dir == 0 ? K.ba[0][n] : K.ba[1][n], bx = dir == 0 ? K.bx[0][n] : K.bx[1][n], sp8 = dir == 0 ? K.sp8[0][n] : K.sp8[1][n];
; #pragma unroll
;         for (int j = 0; j < 4; j++) {
;           int tl = wave * 16 + fq * 4 + j, c2 = n * 16 + fr;
;           float xv = (float)*(const half_t*)(xr16 + swz128(tl, c2));
;           float rg = sigmoidf_(acc[0][n][j] + ba), ig = sigmoidf_(acc[1][n][j] + bx);
;           float log_a = rg * sp8;
;           float x2 = 2.f * log_a;
;           float om = -x2 * (1.f + x2 * (0.5f + x2 * (0.16666667f + x2 * (0.041666668f + x2 * (0.008333334f + x2 * 0.0013888889f)))));
;           if (x2 < -0.4f) { float a = __expf(log_a); om = 1.f - a * a; }
;           ab[tl * 64 + c2] = make_float2(log_a, sqrtf(om) * (ig * xv));
;         }
;       }
	v_cvt_f32_f16_e32 v9, v9
	v_cndmask_b32_e32 v10, v10, v11, vcc
	v_sqrt_f32_e32 v11, v10
	v_mul_f32_e32 v9, v15, v9
	v_add_u32_e32 v12, -1, v11
	v_fma_f32 v13, -v12, v11, v10
	v_cmp_ge_f32_e64 s[0:1], 0, v13
	v_add_u32_e32 v13, 1, v11
	s_nop 0
	v_cndmask_b32_e64 v12, v11, v12, s[0:1]
	v_fma_f32 v11, -v13, v11, v10
	v_cmp_lt_f32_e64 s[0:1], 0, v11
	s_nop 1
	v_cndmask_b32_e64 v11, v12, v13, s[0:1]
	v_mul_f32_e32 v12, 0x37800000, v11
	v_cndmask_b32_e32 v11, v11, v12, vcc
	v_cmp_class_f32_e32 vcc, v10, v178
	s_nop 1
	v_cndmask_b32_e32 v10, v11, v10, vcc
	v_mul_f32_e32 v9, v9, v10
	v_accvgpr_read_b32 v10, a30
	v_add_f32_e32 v10, v14, v10
	v_mul_f32_e32 v10, 0xbfb8aa3b, v10
	v_exp_f32_e32 v10, v10
	ds_write_b64 v62, v[8:9] offset:40960
	ds_read_u16 v8, v63 offset:32768
	v_accvgpr_read_b32 v9, a26
	v_add_f32_e32 v10, 1.0, v10
	v_div_scale_f32 v11, s[0:1], v10, v10, 1.0
	v_rcp_f32_e32 v12, v11
	s_waitcnt lgkmcnt(0)
	v_cvt_f32_f16_e32 v8, v8
	v_add_f32_e32 v9, v7, v9
	v_mul_f32_e32 v9, 0xbfb8aa3b, v9
	v_fma_f32 v13, -v11, v12, 1.0
	v_fmac_f32_e32 v12, v13, v12
	v_div_scale_f32 v13, vcc, 1.0, v10, 1.0
	v_mul_f32_e32 v15, v13, v12
	v_fma_f32 v16, -v11, v15, v13
	v_fmac_f32_e32 v15, v16, v12
	v_fma_f32 v11, -v11, v15, v13
	v_div_fmas_f32 v11, v11, v12, v15
	v_div_fixup_f32 v10, v11, v10, 1.0
	v_mul_f32_e32 v10, v10, v8
	v_accvgpr_read_b32 v8, a27
	v_add_f32_e32 v7, v7, v8
	v_mul_f32_e32 v7, 0xbfb8aa3b, v7
	v_exp_f32_e32 v8, v7
	v_accvgpr_read_b32 v7, a31
	v_add_f32_e32 v7, v14, v7
	v_mul_f32_e32 v7, 0xbfb8aa3b, v7
	v_exp_f32_e32 v7, v7
	v_exp_f32_e32 v9, v9
	v_add_f32_e32 v7, 1.0, v7
	v_div_scale_f32 v11, s[0:1], v7, v7, 1.0
	v_rcp_f32_e32 v12, v11
	v_pk_add_f32 v[8:9], v[8:9], 1.0 op_sel_hi:[1,0]
	v_fma_f32 v13, -v11, v12, 1.0
	v_fmac_f32_e32 v12, v13, v12
	v_div_scale_f32 v13, vcc, 1.0, v7, 1.0
	v_mul_f32_e32 v14, v13, v12
	v_fma_f32 v15, -v11, v14, v13
	v_fmac_f32_e32 v14, v15, v12
	v_fma_f32 v11, -v11, v14, v13
	v_div_fmas_f32 v11, v11, v12, v14
	v_div_fixup_f32 v12, v11, v7, 1.0
	v_div_scale_f32 v7, s[0:1], v9, v9, 1.0
	v_rcp_f32_e32 v11, v7
	s_nop 0
	v_fma_f32 v13, -v7, v11, 1.0
	v_fmac_f32_e32 v11, v13, v11
	v_div_scale_f32 v13, vcc, 1.0, v9, 1.0
	v_mul_f32_e32 v14, v13, v11
	v_fma_f32 v15, -v7, v14, v13
	v_fmac_f32_e32 v14, v15, v11
	v_fma_f32 v7, -v7, v14, v13
	v_div_fmas_f32 v7, v7, v11, v14
	v_div_fixup_f32 v9, v7, v9, 1.0
	v_div_scale_f32 v7, s[0:1], v8, v8, 1.0
	v_rcp_f32_e32 v11, v7
	s_nop 0
	v_fma_f32 v13, -v7, v11, 1.0
	v_fmac_f32_e32 v11, v13, v11
	v_div_scale_f32 v13, vcc, 1.0, v8, 1.0
	v_mul_f32_e32 v14, v13, v11
	v_fma_f32 v15, -v7, v14, v13
	v_fmac_f32_e32 v14, v15, v11
	v_fma_f32 v7, -v7, v14, v13
	v_div_fmas_f32 v7, v7, v11, v14
	v_div_fixup_f32 v8, v7, v8, 1.0
	v_pk_mul_f32 v[6:7], v[6:7], v[8:9] op_sel_hi:[0,1]
	v_pk_add_f32 v[8:9], v[6:7], v[6:7]
	v_mul_f32_e32 v13, 0x3fb8aa3b, v7
	v_fmamk_f32 v11, v9, 0x3ab60b61, v177
	v_fmaak_f32 v11, v9, v11, 0x3d2aaaab
	v_exp_f32_e32 v13, v13
	v_fmaak_f32 v11, v9, v11, 0x3e2aaaab
	v_fma_f32 v11, v9, v11, 0.5
	v_fma_f32 v11, v9, v11, 1.0
	v_mul_f32_e64 v11, v11, -v9
	v_fma_f32 v13, -v13, v13, 1.0
	v_cmp_gt_f32_e64 s[0:1], s41, v9
	v_cmp_gt_f32_e32 vcc, s41, v8
	s_nop 0
	v_cndmask_b32_e64 v9, v11, v13, s[0:1]
	v_cmp_gt_f32_e64 s[0:1], s47, v9
	v_mul_f32_e32 v11, 0x4f800000, v9
	s_nop 0
	v_cndmask_b32_e64 v9, v9, v11, s[0:1]
	v_sqrt_f32_e32 v11, v9
	s_nop 0
	v_add_u32_e32 v13, -1, v11
	v_fma_f32 v14, -v13, v11, v9
	v_cmp_ge_f32_e64 s[6:7], 0, v14
	v_add_u32_e32 v14, 1, v11
	s_nop 0
	v_cndmask_b32_e64 v13, v11, v13, s[6:7]
	v_fma_f32 v11, -v14, v11, v9
	v_cmp_lt_f32_e64 s[6:7], 0, v11
	s_nop 1
	v_cndmask_b32_e64 v11, v13, v14, s[6:7]
	v_mul_f32_e32 v13, 0x37800000, v11
	v_cndmask_b32_e64 v11, v11, v13, s[0:1]
	v_cmp_class_f32_e64 s[0:1], v9, v178
	v_cndmask_b32_e64 v14, v40, v28, s[2:3]
	s_nop 0
	v_cndmask_b32_e64 v9, v11, v9, s[0:1]
	v_mul_f32_e32 v11, v9, v10
	v_fmamk_f32 v9, v8, 0x3ab60b61, v177
	v_fmaak_f32 v9, v8, v9, 0x3d2aaaab
	v_fmaak_f32 v9, v8, v9, 0x3e2aaaab
	v_fma_f32 v9, v8, v9, 0.5
	v_fma_f32 v9, v8, v9, 1.0
	v_mul_f32_e64 v8, v9, -v8
	v_mul_f32_e32 v9, 0x3fb8aa3b, v6
	v_exp_f32_e32 v9, v9
	v_mov_b32_e32 v10, v7
	ds_write_b64 v64, v[10:11] offset:40960
	ds_read_u16 v7, v65 offset:32768
	v_fma_f32 v9, -v9, v9, 1.0
	v_cndmask_b32_e32 v8, v8, v9, vcc
	v_cmp_gt_f32_e32 vcc, s47, v8
	v_mul_f32_e32 v9, 0x4f800000, v8
	s_waitcnt lgkmcnt(0)
	v_cvt_f32_f16_e32 v7, v7
	v_cndmask_b32_e32 v8, v8, v9, vcc
	v_sqrt_f32_e32 v9, v8
	v_mul_f32_e32 v7, v12, v7
	v_add_u32_e32 v10, -1, v9
	v_fma_f32 v11, -v10, v9, v8
	v_cmp_ge_f32_e64 s[0:1], 0, v11
	v_add_u32_e32 v11, 1, v9
	s_nop 0
	v_cndmask_b32_e64 v10, v9, v10, s[0:1]
	v_fma_f32 v9, -v11, v9, v8
	v_cmp_lt_f32_e64 s[0:1], 0, v9
	s_nop 1
	v_cndmask_b32_e64 v9, v10, v11, s[0:1]
	v_mul_f32_e32 v10, 0x37800000, v9
	v_cndmask_b32_e32 v9, v9, v10, vcc
	v_accvgpr_read_b32 v10, a20
	v_add_f32_e32 v10, v14, v10
	v_mul_f32_e32 v10, 0xbfb8aa3b, v10
	v_exp_f32_e32 v10, v10
	v_cmp_class_f32_e32 vcc, v8, v178
	v_add_f32_e32 v10, 1.0, v10
	v_div_scale_f32 v11, s[0:1], v10, v10, 1.0
	v_cndmask_b32_e32 v8, v9, v8, vcc
	v_rcp_f32_e32 v12, v11
	v_mul_f32_e32 v7, v8, v7
	ds_write_b64 v66, v[6:7] offset:40960
	ds_read_u16 v8, v67 offset:32768
	v_fma_f32 v13, -v11, v12, 1.0
	v_fmac_f32_e32 v12, v13, v12
	v_div_scale_f32 v13, vcc, 1.0, v10, 1.0
	v_mul_f32_e32 v15, v13, v12
	v_fma_f32 v16, -v11, v15, v13
	s_waitcnt lgkmcnt(0)
; DI float sigmoidf_(float x) { return 1.f / (1.f + __expf(-x)); }
; DI void lru_tile(const Params& P, int l, int b, int tile, int g, char* smem, bool final, const LruK& K) {
;     ...
; #pragma unroll
;       for (int n = 0; n < 4; n++) {
;         const float ba = dir == 0 ? K.ba[0][n] : K.ba[1][n], bx = dir == 0 ? K.bx[0][n] : K.bx[1][n], sp8 = dir == 0 ? K.sp8[0][n] : K.sp8[1][n];
; #pragma unroll
;         for (int j = 0; j < 4; j++) {
;           int tl = wave * 16 + fq * 4 + j, c2 = n * 16 + fr;
;           float xv = (float)*(const half_t*)(xr16 + swz128(tl, c2));
;           float rg = sigmoidf_(acc[0][n][j] + ba), ig = sigmoidf_(acc[1][n][j] + bx);
;           float log_a = rg * sp8;
;           float x2 = 2.f * log_a;
;           float om = -x2 * (1.f + x2 * (0.5f + x2 * (0.16666667f + x2 * (0.041666668f + x2 * (0.008333334f + x2 * 0.0013888889f)))));
;           if (x2 < -0.4f) { float a = __expf(log_a); om = 1.f - a * a; }
;           ab[tl * 64 + c2] = make_float2(log_a, sqrtf(om) * (ig * xv));
;         }
;       }
	v_cvt_f32_f16_e32 v8, v8
	v_fmac_f32_e32 v15, v16, v12
	v_fma_f32 v11, -v11, v15, v13
	v_div_fmas_f32 v11, v11, v12, v15
	v_div_fixup_f32 v10, v11, v10, 1.0
	v_mul_f32_e32 v12, v10, v8
	v_accvgpr_read_b32 v10, a21
	v_add_f32_e32 v10, v14, v10
	v_mul_f32_e32 v10, 0xbfb8aa3b, v10
	v_exp_f32_e32 v10, v10
	v_cndmask_b32_e64 v7, v39, v27, s[2:3]
	v_accvgpr_read_b32 v9, a16
	v_accvgpr_read_b32 v8, a17
	v_add_f32_e32 v10, 1.0, v10
	v_div_scale_f32 v11, s[0:1], v10, v10, 1.0
	v_rcp_f32_e32 v13, v11
	v_add_f32_e32 v9, v7, v9
	v_add_f32_e32 v8, v7, v8
	v_mul_f32_e32 v9, 0xbfb8aa3b, v9
	v_fma_f32 v15, -v11, v13, 1.0
	v_mul_f32_e32 v8, 0xbfb8aa3b, v8
	v_fmac_f32_e32 v13, v15, v13
	v_div_scale_f32 v15, vcc, 1.0, v10, 1.0
	v_exp_f32_e32 v9, v9
	v_exp_f32_e32 v8, v8
	v_mul_f32_e32 v16, v15, v13
	v_fma_f32 v17, -v11, v16, v15
	v_fmac_f32_e32 v16, v17, v13
	v_fma_f32 v11, -v11, v16, v15
	v_div_fmas_f32 v11, v11, v13, v16
	v_pk_add_f32 v[8:9], v[8:9], 1.0 op_sel_hi:[1,0]
	v_div_fixup_f32 v15, v11, v10, 1.0
	v_div_scale_f32 v10, s[0:1], v9, v9, 1.0
	v_rcp_f32_e32 v11, v10
	v_cndmask_b32_e64 v6, v41, v29, s[2:3]
	v_mul_f32_e32 v6, 0xc1000000, v6
	v_fma_f32 v13, -v10, v11, 1.0
	v_fmac_f32_e32 v11, v13, v11
	v_div_scale_f32 v13, vcc, 1.0, v9, 1.0
	v_mul_f32_e32 v16, v13, v11
	v_fma_f32 v17, -v10, v16, v13
	v_fmac_f32_e32 v16, v17, v11
	v_fma_f32 v10, -v10, v16, v13
	v_div_fmas_f32 v10, v10, v11, v16
	v_div_fixup_f32 v9, v10, v9, 1.0
	v_div_scale_f32 v10, s[0:1], v8, v8, 1.0
	v_rcp_f32_e32 v11, v10
	s_nop 0
	v_fma_f32 v13, -v10, v11, 1.0
	v_fmac_f32_e32 v11, v13, v11
	v_div_scale_f32 v13, vcc, 1.0, v8, 1.0
	v_mul_f32_e32 v16, v13, v11
	v_fma_f32 v17, -v10, v16, v13
	v_fmac_f32_e32 v16, v17, v11
	v_fma_f32 v10, -v10, v16, v13
	v_div_fmas_f32 v10, v10, v11, v16
	v_div_fixup_f32 v8, v10, v8, 1.0
	v_pk_mul_f32 v[8:9], v[6:7], v[8:9] op_sel_hi:[0,1]
	v_pk_add_f32 v[10:11], v[8:9], v[8:9]
	v_mul_f32_e32 v16, 0x3fb8aa3b, v9
	v_fmamk_f32 v13, v11, 0x3ab60b61, v177
	v_fmaak_f32 v13, v11, v13, 0x3d2aaaab
	v_exp_f32_e32 v16, v16
	v_fmaak_f32 v13, v11, v13, 0x3e2aaaab
	v_fma_f32 v13, v11, v13, 0.5
	v_fma_f32 v13, v11, v13, 1.0
	v_mul_f32_e64 v13, v13, -v11
	v_fma_f32 v16, -v16, v16, 1.0
	v_cmp_gt_f32_e64 s[0:1], s41, v11
	v_cmp_gt_f32_e32 vcc, s41, v10
	s_nop 0
	v_cndmask_b32_e64 v11, v13, v16, s[0:1]
	v_cmp_gt_f32_e64 s[0:1], s47, v11
	v_mul_f32_e32 v13, 0x4f800000, v11
	s_nop 0
	v_cndmask_b32_e64 v11, v11, v13, s[0:1]
	v_sqrt_f32_e32 v13, v11
	s_nop 0
	v_add_u32_e32 v16, -1, v13
	v_fma_f32 v17, -v16, v13, v11
	v_cmp_ge_f32_e64 s[6:7], 0, v17
	v_add_u32_e32 v17, 1, v13
	s_nop 0
	v_cndmask_b32_e64 v16, v13, v16, s[6:7]
	v_fma_f32 v13, -v17, v13, v11
	v_cmp_lt_f32_e64 s[6:7], 0, v13
	s_nop 1
	v_cndmask_b32_e64 v13, v16, v17, s[6:7]
	v_mul_f32_e32 v16, 0x37800000, v13
	v_cndmask_b32_e64 v13, v13, v16, s[0:1]
	v_cmp_class_f32_e64 s[0:1], v11, v178
	s_nop 1
	v_cndmask_b32_e64 v11, v13, v11, s[0:1]
	v_mul_f32_e32 v13, v11, v12
	v_fmamk_f32 v11, v10, 0x3ab60b61, v177
	v_fmaak_f32 v11, v10, v11, 0x3d2aaaab
	v_fmaak_f32 v11, v10, v11, 0x3e2aaaab
	v_fma_f32 v11, v10, v11, 0.5
	v_fma_f32 v11, v10, v11, 1.0
	v_mul_f32_e64 v10, v11, -v10
	v_mul_f32_e32 v11, 0x3fb8aa3b, v8
	v_exp_f32_e32 v11, v11
	v_mov_b32_e32 v12, v9
	ds_write_b64 v60, v[12:13] offset:41088
	ds_read_u16 v9, v68 offset:32768
	v_fma_f32 v11, -v11, v11, 1.0
	v_cndmask_b32_e32 v10, v10, v11, vcc
	v_cmp_gt_f32_e32 vcc, s47, v10
	v_mul_f32_e32 v11, 0x4f800000, v10
	s_waitcnt lgkmcnt(0)
	v_cvt_f32_f16_e32 v9, v9
	v_cndmask_b32_e32 v10, v10, v11, vcc
	v_sqrt_f32_e32 v11, v10
	v_mul_f32_e32 v9, v15, v9
	v_add_u32_e32 v12, -1, v11
	v_fma_f32 v13, -v12, v11, v10
	v_cmp_ge_f32_e64 s[0:1], 0, v13
	v_add_u32_e32 v13, 1, v11
	s_nop 0
	v_cndmask_b32_e64 v12, v11, v12, s[0:1]
	v_fma_f32 v11, -v13, v11, v10
	v_cmp_lt_f32_e64 s[0:1], 0, v11
	s_nop 1
	v_cndmask_b32_e64 v11, v12, v13, s[0:1]
	v_mul_f32_e32 v12, 0x37800000, v11
	v_cndmask_b32_e32 v11, v11, v12, vcc
	v_cmp_class_f32_e32 vcc, v10, v178
	s_nop 1
	v_cndmask_b32_e32 v10, v11, v10, vcc
	v_mul_f32_e32 v9, v10, v9
	v_accvgpr_read_b32 v10, a22
	v_add_f32_e32 v10, v14, v10
	v_mul_f32_e32 v10, 0xbfb8aa3b, v10
	v_exp_f32_e32 v10, v10
	ds_write_b64 v62, v[8:9] offset:41088
	ds_read_u16 v8, v69 offset:32768
	v_accvgpr_read_b32 v9, a18
	v_add_f32_e32 v10, 1.0, v10
	v_div_scale_f32 v11, s[0:1], v10, v10, 1.0
	v_rcp_f32_e32 v12, v11
	s_waitcnt lgkmcnt(0)
; DI float sigmoidf_(float x) { return 1.f / (1.f + __expf(-x)); }
; DI void lru_tile(const Params& P, int l, int b, int tile, int g, char* smem, bool final, const LruK& K) {
;     ...
; #pragma unroll
;       for (int n = 0; n < 4; n++) {
;         const float ba = dir == 0 ? K.ba[0][n] : K.ba[1][n], bx = dir == 0 ? K.bx[0][n] : K.bx[1][n], sp8 = dir == 0 ? K.sp8[0][n] : K.sp8[1][n];
; #pragma unroll
;         for (int j = 0; j < 4; j++) {
;           int tl = wave * 16 + fq * 4 + j, c2 = n * 16 + fr;
;           float xv = (float)*(const half_t*)(xr16 + swz128(tl, c2));
;           float rg = sigmoidf_(acc[0][n][j] + ba), ig = sigmoidf_(acc[1][n][j] + bx);
;           float log_a = rg * sp8;
;           float x2 = 2.f * log_a;
;           float om = -x2 * (1.f + x2 * (0.5f + x2 * (0.16666667f + x2 * (0.041666668f + x2 * (0.008333334f + x2 * 0.0013888889f)))));
;           if (x2 < -0.4f) { float a = __expf(log_a); om = 1.f - a * a; }
;           ab[tl * 64 + c2] = make_float2(log_a, sqrtf(om) * (ig * xv));
;         }
;       }
	v_cvt_f32_f16_e32 v8, v8
	v_add_f32_e32 v9, v7, v9
	v_mul_f32_e32 v9, 0xbfb8aa3b, v9
	v_fma_f32 v13, -v11, v12, 1.0
	v_fmac_f32_e32 v12, v13, v12
	v_div_scale_f32 v13, vcc, 1.0, v10, 1.0
	v_mul_f32_e32 v15, v13, v12
	v_fma_f32 v16, -v11, v15, v13
	v_fmac_f32_e32 v15, v16, v12
	v_fma_f32 v11, -v11, v15, v13
	v_div_fmas_f32 v11, v11, v12, v15
	v_div_fixup_f32 v10, v11, v10, 1.0
	v_mul_f32_e32 v10, v10, v8
	v_accvgpr_read_b32 v8, a19
	v_add_f32_e32 v7, v7, v8
	v_mul_f32_e32 v7, 0xbfb8aa3b, v7
	v_exp_f32_e32 v8, v7
	v_accvgpr_read_b32 v7, a23
	v_add_f32_e32 v7, v14, v7
	v_mul_f32_e32 v7, 0xbfb8aa3b, v7
	v_exp_f32_e32 v7, v7
	v_exp_f32_e32 v9, v9
	v_add_f32_e32 v7, 1.0, v7
	v_div_scale_f32 v11, s[0:1], v7, v7, 1.0
	v_rcp_f32_e32 v12, v11
	v_pk_add_f32 v[8:9], v[8:9], 1.0 op_sel_hi:[1,0]
	v_fma_f32 v13, -v11, v12, 1.0
	v_fmac_f32_e32 v12, v13, v12
	v_div_scale_f32 v13, vcc, 1.0, v7, 1.0
	v_mul_f32_e32 v14, v13, v12
	v_fma_f32 v15, -v11, v14, v13
	v_fmac_f32_e32 v14, v15, v12
	v_fma_f32 v11, -v11, v14, v13
	v_div_fmas_f32 v11, v11, v12, v14
	v_div_fixup_f32 v12, v11, v7, 1.0
	v_div_scale_f32 v7, s[0:1], v9, v9, 1.0
	v_rcp_f32_e32 v11, v7
	s_nop 0
	v_fma_f32 v13, -v7, v11, 1.0
	v_fmac_f32_e32 v11, v13, v11
	v_div_scale_f32 v13, vcc, 1.0, v9, 1.0
	v_mul_f32_e32 v14, v13, v11
	v_fma_f32 v15, -v7, v14, v13
	v_fmac_f32_e32 v14, v15, v11
	v_fma_f32 v7, -v7, v14, v13
	v_div_fmas_f32 v7, v7, v11, v14
	v_div_fixup_f32 v9, v7, v9, 1.0
	v_div_scale_f32 v7, s[0:1], v8, v8, 1.0
	v_rcp_f32_e32 v11, v7
	s_nop 0
	v_fma_f32 v13, -v7, v11, 1.0
	v_fmac_f32_e32 v11, v13, v11
	v_div_scale_f32 v13, vcc, 1.0, v8, 1.0
	v_mul_f32_e32 v14, v13, v11
	v_fma_f32 v15, -v7, v14, v13
	v_fmac_f32_e32 v14, v15, v11
	v_fma_f32 v7, -v7, v14, v13
	v_div_fmas_f32 v7, v7, v11, v14
	v_div_fixup_f32 v8, v7, v8, 1.0
	v_pk_mul_f32 v[6:7], v[6:7], v[8:9] op_sel_hi:[0,1]
	v_pk_add_f32 v[8:9], v[6:7], v[6:7]
	v_mul_f32_e32 v13, 0x3fb8aa3b, v7
	v_fmamk_f32 v11, v9, 0x3ab60b61, v177
	v_fmaak_f32 v11, v9, v11, 0x3d2aaaab
	v_exp_f32_e32 v13, v13
	v_fmaak_f32 v11, v9, v11, 0x3e2aaaab
	v_fma_f32 v11, v9, v11, 0.5
	v_fma_f32 v11, v9, v11, 1.0
	v_mul_f32_e64 v11, v11, -v9
	v_fma_f32 v13, -v13, v13, 1.0
	v_cmp_gt_f32_e64 s[0:1], s41, v9
	v_cmp_gt_f32_e32 vcc, s41, v8
	s_nop 0
	v_cndmask_b32_e64 v9, v11, v13, s[0:1]
	v_cmp_gt_f32_e64 s[0:1], s47, v9
	v_mul_f32_e32 v11, 0x4f800000, v9
	s_nop 0
	v_cndmask_b32_e64 v9, v9, v11, s[0:1]
	v_sqrt_f32_e32 v11, v9
	s_nop 0
	v_add_u32_e32 v13, -1, v11
	v_fma_f32 v14, -v13, v11, v9
	v_cmp_ge_f32_e64 s[6:7], 0, v14
	v_add_u32_e32 v14, 1, v11
	s_nop 0
	v_cndmask_b32_e64 v13, v11, v13, s[6:7]
	v_fma_f32 v11, -v14, v11, v9
	v_cmp_lt_f32_e64 s[6:7], 0, v11
	s_nop 1
	v_cndmask_b32_e64 v11, v13, v14, s[6:7]
	v_mul_f32_e32 v13, 0x37800000, v11
	v_cndmask_b32_e64 v11, v11, v13, s[0:1]
	v_cmp_class_f32_e64 s[0:1], v9, v178
	v_cndmask_b32_e64 v14, v43, v31, s[2:3]
	s_nop 0
	v_cndmask_b32_e64 v9, v11, v9, s[0:1]
	v_mul_f32_e32 v11, v9, v10
	v_fmamk_f32 v9, v8, 0x3ab60b61, v177
	v_fmaak_f32 v9, v8, v9, 0x3d2aaaab
	v_fmaak_f32 v9, v8, v9, 0x3e2aaaab
	v_fma_f32 v9, v8, v9, 0.5
	v_fma_f32 v9, v8, v9, 1.0
	v_mul_f32_e64 v8, v9, -v8
	v_mul_f32_e32 v9, 0x3fb8aa3b, v6
	v_exp_f32_e32 v9, v9
	v_mov_b32_e32 v10, v7
	ds_write_b64 v64, v[10:11] offset:41088
	ds_read_u16 v7, v70 offset:32768
	v_fma_f32 v9, -v9, v9, 1.0
	v_cndmask_b32_e32 v8, v8, v9, vcc
	v_cmp_gt_f32_e32 vcc, s47, v8
	v_mul_f32_e32 v9, 0x4f800000, v8
	s_waitcnt lgkmcnt(0)
	v_cvt_f32_f16_e32 v7, v7
	v_cndmask_b32_e32 v8, v8, v9, vcc
	v_sqrt_f32_e32 v9, v8
	v_mul_f32_e32 v7, v12, v7
	v_add_u32_e32 v10, -1, v9
	v_fma_f32 v11, -v10, v9, v8
	v_cmp_ge_f32_e64 s[0:1], 0, v11
	v_add_u32_e32 v11, 1, v9
	s_nop 0
	v_cndmask_b32_e64 v10, v9, v10, s[0:1]
	v_fma_f32 v9, -v11, v9, v8
	v_cmp_lt_f32_e64 s[0:1], 0, v9
	s_nop 1
	v_cndmask_b32_e64 v9, v10, v11, s[0:1]
	v_mul_f32_e32 v10, 0x37800000, v9
	v_cndmask_b32_e32 v9, v9, v10, vcc
	v_accvgpr_read_b32 v10, a12
	v_add_f32_e32 v10, v14, v10
	v_mul_f32_e32 v10, 0xbfb8aa3b, v10
	v_exp_f32_e32 v10, v10
	v_cmp_class_f32_e32 vcc, v8, v178
	v_add_f32_e32 v10, 1.0, v10
	v_div_scale_f32 v11, s[0:1], v10, v10, 1.0
	v_cndmask_b32_e32 v8, v9, v8, vcc
	v_rcp_f32_e32 v12, v11
	v_mul_f32_e32 v7, v8, v7
	ds_write_b64 v66, v[6:7] offset:41088
	ds_read_u16 v8, v71 offset:32768
	v_fma_f32 v13, -v11, v12, 1.0
	v_fmac_f32_e32 v12, v13, v12
	v_div_scale_f32 v13, vcc, 1.0, v10, 1.0
	v_mul_f32_e32 v15, v13, v12
	v_fma_f32 v16, -v11, v15, v13
	s_waitcnt lgkmcnt(0)
; DI float sigmoidf_(float x) { return 1.f / (1.f + __expf(-x)); }
; DI void lru_tile(const Params& P, int l, int b, int tile, int g, char* smem, bool final, const LruK& K) {
;     ...
; #pragma unroll
;       for (int n = 0; n < 4; n++) {
;         const float ba = dir == 0 ? K.ba[0][n] : K.ba[1][n], bx = dir == 0 ? K.bx[0][n] : K.bx[1][n], sp8 = dir == 0 ? K.sp8[0][n] : K.sp8[1][n];
; #pragma unroll
;         for (int j = 0; j < 4; j++) {
;           int tl = wave * 16 + fq * 4 + j, c2 = n * 16 + fr;
;           float xv = (float)*(const half_t*)(xr16 + swz128(tl, c2));
;           float rg = sigmoidf_(acc[0][n][j] + ba), ig = sigmoidf_(acc[1][n][j] + bx);
;           float log_a = rg * sp8;
;           float x2 = 2.f * log_a;
;           float om = -x2 * (1.f + x2 * (0.5f + x2 * (0.16666667f + x2 * (0.041666668f + x2 * (0.008333334f + x2 * 0.0013888889f)))));
;           if (x2 < -0.4f) { float a = __expf(log_a); om = 1.f - a * a; }
;           ab[tl * 64 + c2] = make_float2(log_a, sqrtf(om) * (ig * xv));
;         }
;       }
	v_cvt_f32_f16_e32 v8, v8
	v_fmac_f32_e32 v15, v16, v12
	v_fma_f32 v11, -v11, v15, v13
	v_div_fmas_f32 v11, v11, v12, v15
	v_div_fixup_f32 v10, v11, v10, 1.0
	v_mul_f32_e32 v12, v10, v8
	v_accvgpr_read_b32 v10, a13
	v_add_f32_e32 v10, v14, v10
	v_mul_f32_e32 v10, 0xbfb8aa3b, v10
	v_exp_f32_e32 v10, v10
	v_cndmask_b32_e64 v7, v42, v30, s[2:3]
	v_accvgpr_read_b32 v9, a8
	v_accvgpr_read_b32 v8, a9
	v_add_f32_e32 v10, 1.0, v10
	v_div_scale_f32 v11, s[0:1], v10, v10, 1.0
	v_rcp_f32_e32 v13, v11
	v_add_f32_e32 v9, v7, v9
	v_add_f32_e32 v8, v7, v8
	v_mul_f32_e32 v9, 0xbfb8aa3b, v9
	v_fma_f32 v15, -v11, v13, 1.0
	v_mul_f32_e32 v8, 0xbfb8aa3b, v8
	v_fmac_f32_e32 v13, v15, v13
	v_div_scale_f32 v15, vcc, 1.0, v10, 1.0
	v_exp_f32_e32 v9, v9
	v_exp_f32_e32 v8, v8
	v_mul_f32_e32 v16, v15, v13
	v_fma_f32 v17, -v11, v16, v15
	v_fmac_f32_e32 v16, v17, v13
	v_fma_f32 v11, -v11, v16, v15
	v_div_fmas_f32 v11, v11, v13, v16
	v_pk_add_f32 v[8:9], v[8:9], 1.0 op_sel_hi:[1,0]
	v_div_fixup_f32 v15, v11, v10, 1.0
	v_div_scale_f32 v10, s[0:1], v9, v9, 1.0
	v_rcp_f32_e32 v11, v10
	v_cndmask_b32_e64 v6, v44, v32, s[2:3]
	v_mul_f32_e32 v6, 0xc1000000, v6
	v_fma_f32 v13, -v10, v11, 1.0
	v_fmac_f32_e32 v11, v13, v11
	v_div_scale_f32 v13, vcc, 1.0, v9, 1.0
	v_mul_f32_e32 v16, v13, v11
	v_fma_f32 v17, -v10, v16, v13
	v_fmac_f32_e32 v16, v17, v11
	v_fma_f32 v10, -v10, v16, v13
	v_div_fmas_f32 v10, v10, v11, v16
	v_div_fixup_f32 v9, v10, v9, 1.0
	v_div_scale_f32 v10, s[0:1], v8, v8, 1.0
	v_rcp_f32_e32 v11, v10
	s_nop 0
	v_fma_f32 v13, -v10, v11, 1.0
	v_fmac_f32_e32 v11, v13, v11
	v_div_scale_f32 v13, vcc, 1.0, v8, 1.0
	v_mul_f32_e32 v16, v13, v11
	v_fma_f32 v17, -v10, v16, v13
	v_fmac_f32_e32 v16, v17, v11
	v_fma_f32 v10, -v10, v16, v13
	v_div_fmas_f32 v10, v10, v11, v16
	v_div_fixup_f32 v8, v10, v8, 1.0
	v_pk_mul_f32 v[8:9], v[6:7], v[8:9] op_sel_hi:[0,1]
	v_pk_add_f32 v[10:11], v[8:9], v[8:9]
	v_mul_f32_e32 v16, 0x3fb8aa3b, v9
	v_fmamk_f32 v13, v11, 0x3ab60b61, v177
	v_fmaak_f32 v13, v11, v13, 0x3d2aaaab
	v_exp_f32_e32 v16, v16
	v_fmaak_f32 v13, v11, v13, 0x3e2aaaab
	v_fma_f32 v13, v11, v13, 0.5
	v_fma_f32 v13, v11, v13, 1.0
	v_mul_f32_e64 v13, v13, -v11
	v_fma_f32 v16, -v16, v16, 1.0
	v_cmp_gt_f32_e64 s[0:1], s41, v11
	v_cmp_gt_f32_e32 vcc, s41, v10
	s_nop 0
	v_cndmask_b32_e64 v11, v13, v16, s[0:1]
	v_cmp_gt_f32_e64 s[0:1], s47, v11
	v_mul_f32_e32 v13, 0x4f800000, v11
	s_nop 0
	v_cndmask_b32_e64 v11, v11, v13, s[0:1]
	v_sqrt_f32_e32 v13, v11
	s_nop 0
	v_add_u32_e32 v16, -1, v13
	v_fma_f32 v17, -v16, v13, v11
	v_cmp_ge_f32_e64 s[6:7], 0, v17
	v_add_u32_e32 v17, 1, v13
	s_nop 0
	v_cndmask_b32_e64 v16, v13, v16, s[6:7]
	v_fma_f32 v13, -v17, v13, v11
	v_cmp_lt_f32_e64 s[6:7], 0, v13
	s_nop 1
	v_cndmask_b32_e64 v13, v16, v17, s[6:7]
	v_mul_f32_e32 v16, 0x37800000, v13
	v_cndmask_b32_e64 v13, v13, v16, s[0:1]
	v_cmp_class_f32_e64 s[0:1], v11, v178
	s_nop 1
	v_cndmask_b32_e64 v11, v13, v11, s[0:1]
	v_mul_f32_e32 v13, v11, v12
	v_fmamk_f32 v11, v10, 0x3ab60b61, v177
	v_fmaak_f32 v11, v10, v11, 0x3d2aaaab
	v_fmaak_f32 v11, v10, v11, 0x3e2aaaab
	v_fma_f32 v11, v10, v11, 0.5
	v_fma_f32 v11, v10, v11, 1.0
	v_mul_f32_e64 v10, v11, -v10
	v_mul_f32_e32 v11, 0x3fb8aa3b, v8
	v_exp_f32_e32 v11, v11
	v_mov_b32_e32 v12, v9
	ds_write_b64 v60, v[12:13] offset:41216
	ds_read_u16 v9, v72 offset:32768
	v_fma_f32 v11, -v11, v11, 1.0
	v_cndmask_b32_e32 v10, v10, v11, vcc
	v_cmp_gt_f32_e32 vcc, s47, v10
	v_mul_f32_e32 v11, 0x4f800000, v10
	s_waitcnt lgkmcnt(0)
	v_cvt_f32_f16_e32 v9, v9
	v_cndmask_b32_e32 v10, v10, v11, vcc
	v_sqrt_f32_e32 v11, v10
	v_mul_f32_e32 v9, v15, v9
	v_add_u32_e32 v12, -1, v11
	v_fma_f32 v13, -v12, v11, v10
	v_cmp_ge_f32_e64 s[0:1], 0, v13
	v_add_u32_e32 v13, 1, v11
	s_nop 0
	v_cndmask_b32_e64 v12, v11, v12, s[0:1]
	v_fma_f32 v11, -v13, v11, v10
	v_cmp_lt_f32_e64 s[0:1], 0, v11
	s_nop 1
	v_cndmask_b32_e64 v11, v12, v13, s[0:1]
	v_mul_f32_e32 v12, 0x37800000, v11
	v_cndmask_b32_e32 v11, v11, v12, vcc
	v_cmp_class_f32_e32 vcc, v10, v178
	s_nop 1
	v_cndmask_b32_e32 v10, v11, v10, vcc
	v_mul_f32_e32 v9, v10, v9
	v_accvgpr_read_b32 v10, a14
	v_add_f32_e32 v10, v14, v10
	v_mul_f32_e32 v10, 0xbfb8aa3b, v10
	v_exp_f32_e32 v10, v10
	ds_write_b64 v62, v[8:9] offset:41216
	ds_read_u16 v8, v73 offset:32768
	v_accvgpr_read_b32 v9, a10
	v_add_f32_e32 v10, 1.0, v10
	v_div_scale_f32 v11, s[0:1], v10, v10, 1.0
	v_rcp_f32_e32 v12, v11
	s_waitcnt lgkmcnt(0)
; DI float sigmoidf_(float x) { return 1.f / (1.f + __expf(-x)); }
; DI void lru_tile(const Params& P, int l, int b, int tile, int g, char* smem, bool final, const LruK& K) {
;     ...
; #pragma unroll
;       for (int n = 0; n < 4; n++) {
;         const float ba = dir == 0 ? K.ba[0][n] : K.ba[1][n], bx = dir == 0 ? K.bx[0][n] : K.bx[1][n], sp8 = dir == 0 ? K.sp8[0][n] : K.sp8[1][n];
; #pragma unroll
;         for (int j = 0; j < 4; j++) {
;           int tl = wave * 16 + fq * 4 + j, c2 = n * 16 + fr;
;           float xv = (float)*(const half_t*)(xr16 + swz128(tl, c2));
;           float rg = sigmoidf_(acc[0][n][j] + ba), ig = sigmoidf_(acc[1][n][j] + bx);
;           float log_a = rg * sp8;
;           float x2 = 2.f * log_a;
;           float om = -x2 * (1.f + x2 * (0.5f + x2 * (0.16666667f + x2 * (0.041666668f + x2 * (0.008333334f + x2 * 0.0013888889f)))));
;           if (x2 < -0.4f) { float a = __expf(log_a); om = 1.f - a * a; }
;           ab[tl * 64 + c2] = make_float2(log_a, sqrtf(om) * (ig * xv));
;         }
;       }
	v_cvt_f32_f16_e32 v8, v8
	v_add_f32_e32 v9, v7, v9
	v_mul_f32_e32 v9, 0xbfb8aa3b, v9
	v_fma_f32 v13, -v11, v12, 1.0
	v_fmac_f32_e32 v12, v13, v12
	v_div_scale_f32 v13, vcc, 1.0, v10, 1.0
	v_mul_f32_e32 v15, v13, v12
	v_fma_f32 v16, -v11, v15, v13
	v_fmac_f32_e32 v15, v16, v12
	v_fma_f32 v11, -v11, v15, v13
	v_div_fmas_f32 v11, v11, v12, v15
	v_div_fixup_f32 v10, v11, v10, 1.0
	v_mul_f32_e32 v10, v10, v8
	v_accvgpr_read_b32 v8, a11
	v_add_f32_e32 v7, v7, v8
	v_mul_f32_e32 v7, 0xbfb8aa3b, v7
	v_exp_f32_e32 v8, v7
	v_accvgpr_read_b32 v7, a15
	v_add_f32_e32 v7, v14, v7
	v_mul_f32_e32 v7, 0xbfb8aa3b, v7
	v_exp_f32_e32 v7, v7
	v_exp_f32_e32 v9, v9
	v_add_f32_e32 v7, 1.0, v7
	v_div_scale_f32 v11, s[0:1], v7, v7, 1.0
	v_rcp_f32_e32 v12, v11
	v_pk_add_f32 v[8:9], v[8:9], 1.0 op_sel_hi:[1,0]
	v_fma_f32 v13, -v11, v12, 1.0
	v_fmac_f32_e32 v12, v13, v12
	v_div_scale_f32 v13, vcc, 1.0, v7, 1.0
	v_mul_f32_e32 v14, v13, v12
	v_fma_f32 v15, -v11, v14, v13
	v_fmac_f32_e32 v14, v15, v12
	v_fma_f32 v11, -v11, v14, v13
	v_div_fmas_f32 v11, v11, v12, v14
	v_div_fixup_f32 v12, v11, v7, 1.0
	v_div_scale_f32 v7, s[0:1], v9, v9, 1.0
	v_rcp_f32_e32 v11, v7
	s_nop 0
	v_fma_f32 v13, -v7, v11, 1.0
	v_fmac_f32_e32 v11, v13, v11
	v_div_scale_f32 v13, vcc, 1.0, v9, 1.0
	v_mul_f32_e32 v14, v13, v11
	v_fma_f32 v15, -v7, v14, v13
	v_fmac_f32_e32 v14, v15, v11
	v_fma_f32 v7, -v7, v14, v13
	v_div_fmas_f32 v7, v7, v11, v14
	v_div_fixup_f32 v9, v7, v9, 1.0
	v_div_scale_f32 v7, s[0:1], v8, v8, 1.0
	v_rcp_f32_e32 v11, v7
	s_nop 0
	v_fma_f32 v13, -v7, v11, 1.0
	v_fmac_f32_e32 v11, v13, v11
	v_div_scale_f32 v13, vcc, 1.0, v8, 1.0
	v_mul_f32_e32 v14, v13, v11
	v_fma_f32 v15, -v7, v14, v13
	v_fmac_f32_e32 v14, v15, v11
	v_fma_f32 v7, -v7, v14, v13
	v_div_fmas_f32 v7, v7, v11, v14
	v_div_fixup_f32 v8, v7, v8, 1.0
	v_pk_mul_f32 v[6:7], v[6:7], v[8:9] op_sel_hi:[0,1]
	v_pk_add_f32 v[8:9], v[6:7], v[6:7]
	v_mul_f32_e32 v13, 0x3fb8aa3b, v7
	v_fmamk_f32 v11, v9, 0x3ab60b61, v177
	v_fmaak_f32 v11, v9, v11, 0x3d2aaaab
	v_exp_f32_e32 v13, v13
	v_fmaak_f32 v11, v9, v11, 0x3e2aaaab
	v_fma_f32 v11, v9, v11, 0.5
	v_fma_f32 v11, v9, v11, 1.0
	v_mul_f32_e64 v11, v11, -v9
	v_fma_f32 v13, -v13, v13, 1.0
	v_cmp_gt_f32_e64 s[0:1], s41, v9
	v_cmp_gt_f32_e32 vcc, s41, v8
	s_nop 0
	v_cndmask_b32_e64 v9, v11, v13, s[0:1]
	v_cmp_gt_f32_e64 s[0:1], s47, v9
	v_mul_f32_e32 v11, 0x4f800000, v9
	s_nop 0
	v_cndmask_b32_e64 v9, v9, v11, s[0:1]
	v_sqrt_f32_e32 v11, v9
	s_nop 0
	v_add_u32_e32 v13, -1, v11
	v_fma_f32 v14, -v13, v11, v9
	v_cmp_ge_f32_e64 s[6:7], 0, v14
	v_add_u32_e32 v14, 1, v11
	s_nop 0
	v_cndmask_b32_e64 v13, v11, v13, s[6:7]
	v_fma_f32 v11, -v14, v11, v9
	v_cmp_lt_f32_e64 s[6:7], 0, v11
	s_nop 1
	v_cndmask_b32_e64 v11, v13, v14, s[6:7]
	v_mul_f32_e32 v13, 0x37800000, v11
	v_cndmask_b32_e64 v11, v11, v13, s[0:1]
	v_cmp_class_f32_e64 s[0:1], v9, v178
	v_cndmask_b32_e64 v14, v46, v34, s[2:3]
	s_nop 0
	v_cndmask_b32_e64 v9, v11, v9, s[0:1]
	v_mul_f32_e32 v11, v9, v10
	v_fmamk_f32 v9, v8, 0x3ab60b61, v177
	v_fmaak_f32 v9, v8, v9, 0x3d2aaaab
	v_fmaak_f32 v9, v8, v9, 0x3e2aaaab
	v_fma_f32 v9, v8, v9, 0.5
	v_fma_f32 v9, v8, v9, 1.0
	v_mul_f32_e64 v8, v9, -v8
	v_mul_f32_e32 v9, 0x3fb8aa3b, v6
	v_exp_f32_e32 v9, v9
	v_mov_b32_e32 v10, v7
	ds_write_b64 v64, v[10:11] offset:41216
	ds_read_u16 v7, v74 offset:32768
	v_fma_f32 v9, -v9, v9, 1.0
	v_cndmask_b32_e32 v8, v8, v9, vcc
	v_cmp_gt_f32_e32 vcc, s47, v8
	v_mul_f32_e32 v9, 0x4f800000, v8
	s_waitcnt lgkmcnt(0)
	v_cvt_f32_f16_e32 v7, v7
	v_cndmask_b32_e32 v8, v8, v9, vcc
	v_sqrt_f32_e32 v9, v8
	v_mul_f32_e32 v7, v12, v7
	v_add_u32_e32 v10, -1, v9
	v_fma_f32 v11, -v10, v9, v8
	v_cmp_ge_f32_e64 s[0:1], 0, v11
	v_add_u32_e32 v11, 1, v9
	s_nop 0
	v_cndmask_b32_e64 v10, v9, v10, s[0:1]
	v_fma_f32 v9, -v11, v9, v8
	v_cmp_lt_f32_e64 s[0:1], 0, v9
	s_nop 1
	v_cndmask_b32_e64 v9, v10, v11, s[0:1]
	v_mul_f32_e32 v10, 0x37800000, v9
	v_cndmask_b32_e32 v9, v9, v10, vcc
	v_accvgpr_read_b32 v10, a4
	v_add_f32_e32 v10, v14, v10
	v_mul_f32_e32 v10, 0xbfb8aa3b, v10
	v_exp_f32_e32 v10, v10
	v_cmp_class_f32_e32 vcc, v8, v178
	v_add_f32_e32 v10, 1.0, v10
	v_div_scale_f32 v11, s[0:1], v10, v10, 1.0
	v_cndmask_b32_e32 v8, v9, v8, vcc
	v_rcp_f32_e32 v12, v11
	v_mul_f32_e32 v7, v8, v7
	ds_write_b64 v66, v[6:7] offset:41216
	ds_read_u16 v8, v75 offset:32768
	v_fma_f32 v13, -v11, v12, 1.0
	v_fmac_f32_e32 v12, v13, v12
	v_div_scale_f32 v13, vcc, 1.0, v10, 1.0
	v_mul_f32_e32 v15, v13, v12
	v_fma_f32 v16, -v11, v15, v13
	s_waitcnt lgkmcnt(0)
; DI float sigmoidf_(float x) { return 1.f / (1.f + __expf(-x)); }
; DI void lru_tile(const Params& P, int l, int b, int tile, int g, char* smem, bool final, const LruK& K) {
;     ...
; #pragma unroll
;       for (int n = 0; n < 4; n++) {
;         const float ba = dir == 0 ? K.ba[0][n] : K.ba[1][n], bx = dir == 0 ? K.bx[0][n] : K.bx[1][n], sp8 = dir == 0 ? K.sp8[0][n] : K.sp8[1][n];
; #pragma unroll
;         for (int j = 0; j < 4; j++) {
;           int tl = wave * 16 + fq * 4 + j, c2 = n * 16 + fr;
;           float xv = (float)*(const half_t*)(xr16 + swz128(tl, c2));
;           float rg = sigmoidf_(acc[0][n][j] + ba), ig = sigmoidf_(acc[1][n][j] + bx);
;           float log_a = rg * sp8;
;           float x2 = 2.f * log_a;
;           float om = -x2 * (1.f + x2 * (0.5f + x2 * (0.16666667f + x2 * (0.041666668f + x2 * (0.008333334f + x2 * 0.0013888889f)))));
;           if (x2 < -0.4f) { float a = __expf(log_a); om = 1.f - a * a; }
;           ab[tl * 64 + c2] = make_float2(log_a, sqrtf(om) * (ig * xv));
;         }
;       }
	v_cvt_f32_f16_e32 v8, v8
	v_fmac_f32_e32 v15, v16, v12
	v_fma_f32 v11, -v11, v15, v13
	v_div_fmas_f32 v11, v11, v12, v15
	v_div_fixup_f32 v10, v11, v10, 1.0
	v_mul_f32_e32 v12, v10, v8
	v_accvgpr_read_b32 v10, a5
	v_add_f32_e32 v10, v14, v10
	v_mul_f32_e32 v10, 0xbfb8aa3b, v10
	v_exp_f32_e32 v10, v10
	v_cndmask_b32_e64 v7, v45, v33, s[2:3]
	v_accvgpr_read_b32 v9, a0
	v_accvgpr_read_b32 v8, a1
	v_add_f32_e32 v10, 1.0, v10
	v_div_scale_f32 v11, s[0:1], v10, v10, 1.0
	v_rcp_f32_e32 v13, v11
	v_add_f32_e32 v9, v7, v9
	v_add_f32_e32 v8, v7, v8
	v_mul_f32_e32 v9, 0xbfb8aa3b, v9
	v_fma_f32 v15, -v11, v13, 1.0
	v_mul_f32_e32 v8, 0xbfb8aa3b, v8
	v_fmac_f32_e32 v13, v15, v13
	v_div_scale_f32 v15, vcc, 1.0, v10, 1.0
	v_exp_f32_e32 v9, v9
	v_exp_f32_e32 v8, v8
	v_mul_f32_e32 v16, v15, v13
	v_fma_f32 v17, -v11, v16, v15
	v_fmac_f32_e32 v16, v17, v13
	v_fma_f32 v11, -v11, v16, v15
	v_div_fmas_f32 v11, v11, v13, v16
	v_pk_add_f32 v[8:9], v[8:9], 1.0 op_sel_hi:[1,0]
	v_div_fixup_f32 v15, v11, v10, 1.0
	v_div_scale_f32 v10, s[0:1], v9, v9, 1.0
	v_rcp_f32_e32 v11, v10
	v_cndmask_b32_e64 v6, v47, v35, s[2:3]
	v_mul_f32_e32 v6, 0xc1000000, v6
	v_fma_f32 v13, -v10, v11, 1.0
	v_fmac_f32_e32 v11, v13, v11
	v_div_scale_f32 v13, vcc, 1.0, v9, 1.0
	v_mul_f32_e32 v16, v13, v11
	v_fma_f32 v17, -v10, v16, v13
	v_fmac_f32_e32 v16, v17, v11
	v_fma_f32 v10, -v10, v16, v13
	v_div_fmas_f32 v10, v10, v11, v16
	v_div_fixup_f32 v9, v10, v9, 1.0
	v_div_scale_f32 v10, s[0:1], v8, v8, 1.0
	v_rcp_f32_e32 v11, v10
	s_nop 0
	v_fma_f32 v13, -v10, v11, 1.0
	v_fmac_f32_e32 v11, v13, v11
	v_div_scale_f32 v13, vcc, 1.0, v8, 1.0
	v_mul_f32_e32 v16, v13, v11
	v_fma_f32 v17, -v10, v16, v13
	v_fmac_f32_e32 v16, v17, v11
	v_fma_f32 v10, -v10, v16, v13
	v_div_fmas_f32 v10, v10, v11, v16
	v_div_fixup_f32 v8, v10, v8, 1.0
	v_pk_mul_f32 v[8:9], v[6:7], v[8:9] op_sel_hi:[0,1]
	v_pk_add_f32 v[10:11], v[8:9], v[8:9]
	v_mul_f32_e32 v16, 0x3fb8aa3b, v9
	v_fmamk_f32 v13, v11, 0x3ab60b61, v177
	v_fmaak_f32 v13, v11, v13, 0x3d2aaaab
	v_exp_f32_e32 v16, v16
	v_fmaak_f32 v13, v11, v13, 0x3e2aaaab
	v_fma_f32 v13, v11, v13, 0.5
	v_fma_f32 v13, v11, v13, 1.0
	v_mul_f32_e64 v13, v13, -v11
	v_fma_f32 v16, -v16, v16, 1.0
	v_cmp_gt_f32_e64 s[0:1], s41, v11
	v_cmp_gt_f32_e32 vcc, s41, v10
	s_nop 0
	v_cndmask_b32_e64 v11, v13, v16, s[0:1]
	v_cmp_gt_f32_e64 s[0:1], s47, v11
	v_mul_f32_e32 v13, 0x4f800000, v11
	s_nop 0
	v_cndmask_b32_e64 v11, v11, v13, s[0:1]
	v_sqrt_f32_e32 v13, v11
	s_nop 0
	v_add_u32_e32 v16, -1, v13
	v_fma_f32 v17, -v16, v13, v11
	v_cmp_ge_f32_e64 s[6:7], 0, v17
	v_add_u32_e32 v17, 1, v13
	s_nop 0
	v_cndmask_b32_e64 v16, v13, v16, s[6:7]
	v_fma_f32 v13, -v17, v13, v11
	v_cmp_lt_f32_e64 s[6:7], 0, v13
	s_nop 1
	v_cndmask_b32_e64 v13, v16, v17, s[6:7]
	v_mul_f32_e32 v16, 0x37800000, v13
	v_cndmask_b32_e64 v13, v13, v16, s[0:1]
	v_cmp_class_f32_e64 s[0:1], v11, v178
	s_nop 1
	v_cndmask_b32_e64 v11, v13, v11, s[0:1]
	v_mul_f32_e32 v13, v11, v12
	v_fmamk_f32 v11, v10, 0x3ab60b61, v177
	v_fmaak_f32 v11, v10, v11, 0x3d2aaaab
	v_fmaak_f32 v11, v10, v11, 0x3e2aaaab
	v_fma_f32 v11, v10, v11, 0.5
	v_fma_f32 v11, v10, v11, 1.0
	v_mul_f32_e64 v10, v11, -v10
	v_mul_f32_e32 v11, 0x3fb8aa3b, v8
	v_exp_f32_e32 v11, v11
	v_mov_b32_e32 v12, v9
	ds_write_b64 v60, v[12:13] offset:41344
	ds_read_u16 v9, v76 offset:32768
	v_fma_f32 v11, -v11, v11, 1.0
	v_cndmask_b32_e32 v10, v10, v11, vcc
	v_cmp_gt_f32_e32 vcc, s47, v10
	v_mul_f32_e32 v11, 0x4f800000, v10
	s_waitcnt lgkmcnt(0)
	v_cvt_f32_f16_e32 v9, v9
	v_cndmask_b32_e32 v10, v10, v11, vcc
	v_sqrt_f32_e32 v11, v10
	v_mul_f32_e32 v9, v15, v9
	v_add_u32_e32 v12, -1, v11
	v_fma_f32 v13, -v12, v11, v10
	v_cmp_ge_f32_e64 s[0:1], 0, v13
	v_add_u32_e32 v13, 1, v11
	s_nop 0
	v_cndmask_b32_e64 v12, v11, v12, s[0:1]
	v_fma_f32 v11, -v13, v11, v10
	v_cmp_lt_f32_e64 s[0:1], 0, v11
	s_nop 1
	v_cndmask_b32_e64 v11, v12, v13, s[0:1]
	v_mul_f32_e32 v12, 0x37800000, v11
	v_cndmask_b32_e32 v11, v11, v12, vcc
	v_cmp_class_f32_e32 vcc, v10, v178
	s_nop 1
	v_cndmask_b32_e32 v10, v11, v10, vcc
	v_mul_f32_e32 v9, v10, v9
	v_accvgpr_read_b32 v10, a6
	v_add_f32_e32 v10, v14, v10
	v_mul_f32_e32 v10, 0xbfb8aa3b, v10
	v_exp_f32_e32 v10, v10
	ds_write_b64 v62, v[8:9] offset:41344
	ds_read_u16 v8, v77 offset:32768
	v_accvgpr_read_b32 v9, a2
	v_add_f32_e32 v10, 1.0, v10
	v_div_scale_f32 v11, s[0:1], v10, v10, 1.0
	v_rcp_f32_e32 v12, v11
	s_waitcnt lgkmcnt(0)
; DI float sigmoidf_(float x) { return 1.f / (1.f + __expf(-x)); }
; DI void lru_tile(const Params& P, int l, int b, int tile, int g, char* smem, bool final, const LruK& K) {
;     ...
; #pragma unroll
;       for (int n = 0; n < 4; n++) {
;         const float ba = dir == 0 ? K.ba[0][n] : K.ba[1][n], bx = dir == 0 ? K.bx[0][n] : K.bx[1][n], sp8 = dir == 0 ? K.sp8[0][n] : K.sp8[1][n];
; #pragma unroll
;         for (int j = 0; j < 4; j++) {
;           int tl = wave * 16 + fq * 4 + j, c2 = n * 16 + fr;
;           float xv = (float)*(const half_t*)(xr16 + swz128(tl, c2));
;           float rg = sigmoidf_(acc[0][n][j] + ba), ig = sigmoidf_(acc[1][n][j] + bx);
;           float log_a = rg * sp8;
;           float x2 = 2.f * log_a;
;           float om = -x2 * (1.f + x2 * (0.5f + x2 * (0.16666667f + x2 * (0.041666668f + x2 * (0.008333334f + x2 * 0.0013888889f)))));
;           if (x2 < -0.4f) { float a = __expf(log_a); om = 1.f - a * a; }
;           ab[tl * 64 + c2] = make_float2(log_a, sqrtf(om) * (ig * xv));
;         }
;       }
;     }
;     __syncthreads();
;     {
;       float A = 1.f, h = 0.f;
; #pragma unroll
;       for (int e = 0; e < 16; e++) {
;         const int ee = dir == 0 ? e : 15 - e;
;         const float2 lb = ab[(tq * 16 + ee) * 64 + ch];
;         fp16x2 hv; hv[0] = (__fp16)lb.x; hv[1] = (__fp16)lb.y;
;         lab[((size_t)dir * TA + rowbase + t0 + tq * 16 + ee) * 256 + gc] = __builtin_bit_cast(unsigned, hv);
;         const float a = __expf((float)hv[0]), bt = (float)hv[1];
;         h = a * h + bt; A *= a;
	v_cvt_f32_f16_e32 v8, v8
	v_add_f32_e32 v9, v7, v9
	v_mul_f32_e32 v9, 0xbfb8aa3b, v9
	v_fma_f32 v13, -v11, v12, 1.0
	v_fmac_f32_e32 v12, v13, v12
	v_div_scale_f32 v13, vcc, 1.0, v10, 1.0
	v_mul_f32_e32 v15, v13, v12
	v_fma_f32 v16, -v11, v15, v13
	v_fmac_f32_e32 v15, v16, v12
	v_fma_f32 v11, -v11, v15, v13
	v_div_fmas_f32 v11, v11, v12, v15
	v_div_fixup_f32 v10, v11, v10, 1.0
	v_mul_f32_e32 v10, v10, v8
	v_accvgpr_read_b32 v8, a3
	v_add_f32_e32 v7, v7, v8
	v_mul_f32_e32 v7, 0xbfb8aa3b, v7
	v_exp_f32_e32 v8, v7
	v_accvgpr_read_b32 v7, a7
	v_add_f32_e32 v7, v14, v7
	v_mul_f32_e32 v7, 0xbfb8aa3b, v7
	v_exp_f32_e32 v7, v7
	v_exp_f32_e32 v9, v9
	v_add_f32_e32 v7, 1.0, v7
	v_div_scale_f32 v11, s[0:1], v7, v7, 1.0
	v_rcp_f32_e32 v12, v11
	v_pk_add_f32 v[8:9], v[8:9], 1.0 op_sel_hi:[1,0]
	v_fma_f32 v13, -v11, v12, 1.0
	v_fmac_f32_e32 v12, v13, v12
	v_div_scale_f32 v13, vcc, 1.0, v7, 1.0
	v_mul_f32_e32 v14, v13, v12
	v_fma_f32 v15, -v11, v14, v13
	v_fmac_f32_e32 v14, v15, v12
	v_fma_f32 v11, -v11, v14, v13
	v_div_fmas_f32 v11, v11, v12, v14
	v_div_fixup_f32 v12, v11, v7, 1.0
	v_div_scale_f32 v7, s[0:1], v9, v9, 1.0
	v_rcp_f32_e32 v11, v7
	s_nop 0
	v_fma_f32 v13, -v7, v11, 1.0
	v_fmac_f32_e32 v11, v13, v11
	v_div_scale_f32 v13, vcc, 1.0, v9, 1.0
	v_mul_f32_e32 v14, v13, v11
	v_fma_f32 v15, -v7, v14, v13
	v_fmac_f32_e32 v14, v15, v11
	v_fma_f32 v7, -v7, v14, v13
	v_div_fmas_f32 v7, v7, v11, v14
	v_div_fixup_f32 v9, v7, v9, 1.0
	v_div_scale_f32 v7, s[0:1], v8, v8, 1.0
	v_rcp_f32_e32 v11, v7
	s_nop 0
	v_fma_f32 v13, -v7, v11, 1.0
	v_fmac_f32_e32 v11, v13, v11
	v_div_scale_f32 v13, vcc, 1.0, v8, 1.0
	v_mul_f32_e32 v14, v13, v11
	v_fma_f32 v15, -v7, v14, v13
	v_fmac_f32_e32 v14, v15, v11
	v_fma_f32 v7, -v7, v14, v13
	v_div_fmas_f32 v7, v7, v11, v14
	v_div_fixup_f32 v8, v7, v8, 1.0
	v_pk_mul_f32 v[6:7], v[6:7], v[8:9] op_sel_hi:[0,1]
	v_pk_add_f32 v[8:9], v[6:7], v[6:7]
	v_mul_f32_e32 v13, 0x3fb8aa3b, v7
	v_fmamk_f32 v11, v9, 0x3ab60b61, v177
	v_fmaak_f32 v11, v9, v11, 0x3d2aaaab
	v_exp_f32_e32 v13, v13
	v_fmaak_f32 v11, v9, v11, 0x3e2aaaab
	v_fma_f32 v11, v9, v11, 0.5
	v_fma_f32 v11, v9, v11, 1.0
	v_mul_f32_e64 v11, v11, -v9
	v_fma_f32 v13, -v13, v13, 1.0
	v_cmp_gt_f32_e64 s[0:1], s41, v9
	v_cmp_gt_f32_e32 vcc, s41, v8
	s_nop 0
	v_cndmask_b32_e64 v9, v11, v13, s[0:1]
	v_cmp_gt_f32_e64 s[0:1], s47, v9
	v_mul_f32_e32 v11, 0x4f800000, v9
	s_nop 0
	v_cndmask_b32_e64 v9, v9, v11, s[0:1]
	v_sqrt_f32_e32 v11, v9
	s_nop 0
	v_add_u32_e32 v13, -1, v11
	v_fma_f32 v14, -v13, v11, v9
	v_cmp_ge_f32_e64 s[6:7], 0, v14
	v_add_u32_e32 v14, 1, v11
	s_nop 0
	v_cndmask_b32_e64 v13, v11, v13, s[6:7]
	v_fma_f32 v11, -v14, v11, v9
	v_cmp_lt_f32_e64 s[6:7], 0, v11
	s_nop 1
	v_cndmask_b32_e64 v11, v13, v14, s[6:7]
	v_mul_f32_e32 v13, 0x37800000, v11
	v_cndmask_b32_e64 v11, v11, v13, s[0:1]
	v_cmp_class_f32_e64 s[0:1], v9, v178
	s_nop 1
	v_cndmask_b32_e64 v9, v11, v9, s[0:1]
	v_mul_f32_e32 v11, v9, v10
	v_fmamk_f32 v9, v8, 0x3ab60b61, v177
	v_fmaak_f32 v9, v8, v9, 0x3d2aaaab
	v_fmaak_f32 v9, v8, v9, 0x3e2aaaab
	v_fma_f32 v9, v8, v9, 0.5
	v_fma_f32 v9, v8, v9, 1.0
	v_mul_f32_e64 v8, v9, -v8
	v_mul_f32_e32 v9, 0x3fb8aa3b, v6
	v_exp_f32_e32 v9, v9
	v_mov_b32_e32 v10, v7
	ds_write_b64 v64, v[10:11] offset:41344
	ds_read_u16 v7, v78 offset:32768
	v_fma_f32 v9, -v9, v9, 1.0
	v_cndmask_b32_e32 v8, v8, v9, vcc
	v_cmp_gt_f32_e32 vcc, s47, v8
	v_mul_f32_e32 v9, 0x4f800000, v8
	s_waitcnt lgkmcnt(0)
	v_cvt_f32_f16_e32 v7, v7
	v_cndmask_b32_e32 v8, v8, v9, vcc
	v_sqrt_f32_e32 v9, v8
	v_mul_f32_e32 v7, v12, v7
	v_add_u32_e32 v10, -1, v9
	v_fma_f32 v11, -v10, v9, v8
	v_cmp_ge_f32_e64 s[0:1], 0, v11
	v_add_u32_e32 v11, 1, v9
	s_nop 0
	v_cndmask_b32_e64 v10, v9, v10, s[0:1]
	v_fma_f32 v9, -v11, v9, v8
	v_cmp_lt_f32_e64 s[0:1], 0, v9
	s_nop 1
	v_cndmask_b32_e64 v9, v10, v11, s[0:1]
	s_mul_i32 s0, s20, 0x10800
	v_mul_f32_e32 v10, 0x37800000, v9
	s_add_i32 s84, s0, s10
	v_cndmask_b32_e32 v9, v9, v10, vcc
	v_cmp_class_f32_e32 vcc, v8, v178
	s_and_b64 s[0:1], s[2:3], exec
	s_cselect_b32 s0, 0, 15
	v_cndmask_b32_e32 v8, v9, v8, vcc
	v_mul_f32_e32 v7, v8, v7
	v_or_b32_e32 v8, s0, v0
	v_lshl_or_b32 v8, v8, 9, v56
	ds_write_b64 v66, v[6:7] offset:41344
	s_waitcnt lgkmcnt(0)
	s_barrier
	ds_read_b64 v[8:9], v8 offset:40960
	v_lshl_add_u64 v[6:7], v[2:3], 0, s[84:85]
	s_waitcnt lgkmcnt(0)
	v_cvt_f16_f32_e32 v10, v8
	v_cvt_f16_f32_e32 v11, v9
	v_cvt_pk_f16_f32 v12, v8, v9
	v_or_b32_e32 v8, s0, v6
	v_mov_b32_e32 v9, v7
	v_lshlrev_b64 v[8:9], 10, v[8:9]
	v_lshl_add_u64 v[8:9], v[4:5], 0, v[8:9]
	global_store_dword v[8:9], v12, off nt
	v_cvt_f32_f16_e32 v8, v10
	s_cselect_b32 s0, 1, 14
	v_mul_f32_e32 v8, 0x3fb8aa3b, v8
	v_exp_f32_e32 v10, v8
	v_or_b32_e32 v8, s0, v0
	v_lshl_or_b32 v8, v8, 9, v56
	ds_read_b64 v[8:9], v8 offset:40960
	v_fma_mix_f32 v11, v10, 0, v11 op_sel_hi:[0,0,1]
	s_waitcnt lgkmcnt(0)
	v_cvt_f16_f32_e32 v12, v8
	v_cvt_f16_f32_e32 v13, v9
	v_cvt_pk_f16_f32 v14, v8, v9
	v_or_b32_e32 v8, s0, v6
	v_mov_b32_e32 v9, v7
	v_lshlrev_b64 v[8:9], 10, v[8:9]
	v_lshl_add_u64 v[8:9], v[4:5], 0, v[8:9]
	global_store_dword v[8:9], v14, off nt
	v_cvt_f32_f16_e32 v8, v12
	s_cselect_b32 s0, 2, 13
	v_mul_f32_e32 v8, 0x3fb8aa3b, v8
	v_exp_f32_e32 v8, v8
	s_nop 0
	v_fma_mix_f32 v11, v11, v8, v13 op_sel_hi:[0,0,1]
	v_mul_f32_e32 v14, v10, v8
	v_or_b32_e32 v8, s0, v0
	v_lshl_or_b32 v8, v8, 9, v56
	ds_read_b64 v[8:9], v8 offset:40960
	s_waitcnt lgkmcnt(0)
; DI void lru_tile(const Params& P, int l, int b, int tile, int g, char* smem, bool final, const LruK& K) {
;     ...
;     {
;       float A = 1.f, h = 0.f;
; #pragma unroll
;       for (int e = 0; e < 16; e++) {
;         const int ee = dir == 0 ? e : 15 - e;
;         const float2 lb = ab[(tq * 16 + ee) * 64 + ch];
;         fp16x2 hv; hv[0] = (__fp16)lb.x; hv[1] = (__fp16)lb.y;
;         lab[((size_t)dir * TA + rowbase + t0 + tq * 16 + ee) * 256 + gc] = __builtin_bit_cast(unsigned, hv);
;         const float a = __expf((float)hv[0]), bt = (float)hv[1];
;         h = a * h + bt; A *= a;
;       }
	v_cvt_f16_f32_e32 v10, v8
	v_cvt_f16_f32_e32 v12, v9
	v_cvt_pk_f16_f32 v13, v8, v9
	v_or_b32_e32 v8, s0, v6
	v_mov_b32_e32 v9, v7
	v_lshlrev_b64 v[8:9], 10, v[8:9]
	v_lshl_add_u64 v[8:9], v[4:5], 0, v[8:9]
	global_store_dword v[8:9], v13, off nt
	v_cvt_f32_f16_e32 v8, v10
	s_cselect_b32 s0, 3, 12
	v_or_b32_e32 v10, s0, v0
	v_lshl_or_b32 v10, v10, 9, v56
	v_mul_f32_e32 v8, 0x3fb8aa3b, v8
	v_exp_f32_e32 v8, v8
	s_nop 0
	v_fma_mix_f32 v9, v11, v8, v12 op_sel_hi:[0,0,1]
	ds_read_b64 v[10:11], v10 offset:40960
	s_waitcnt lgkmcnt(0)
	v_cvt_f16_f32_e32 v12, v10
	v_cvt_f16_f32_e32 v13, v11
	v_cvt_pk_f16_f32 v15, v10, v11
	v_or_b32_e32 v10, s0, v6
	v_mov_b32_e32 v11, v7
	v_lshlrev_b64 v[10:11], 10, v[10:11]
	v_lshl_add_u64 v[10:11], v[4:5], 0, v[10:11]
	global_store_dword v[10:11], v15, off nt
	v_cvt_f32_f16_e32 v10, v12
	s_cselect_b32 s0, 4, 11
	v_mul_f32_e32 v10, 0x3fb8aa3b, v10
	v_exp_f32_e32 v20, v10
	v_or_b32_e32 v10, s0, v0
	v_lshl_or_b32 v10, v10, 9, v56
	ds_read_b64 v[10:11], v10 offset:40960
	v_fma_mix_f32 v9, v9, v20, v13 op_sel_hi:[0,0,1]
	s_waitcnt lgkmcnt(0)
	v_cvt_f16_f32_e32 v12, v10
	v_cvt_f16_f32_e32 v13, v11
	v_cvt_pk_f16_f32 v15, v10, v11
	v_or_b32_e32 v10, s0, v6
	v_mov_b32_e32 v11, v7
	v_lshlrev_b64 v[10:11], 10, v[10:11]
	v_lshl_add_u64 v[10:11], v[4:5], 0, v[10:11]
	global_store_dword v[10:11], v15, off nt
	v_cvt_f32_f16_e32 v10, v12
	s_cselect_b32 s0, 5, 10
	v_or_b32_e32 v11, s0, v0
	v_lshl_or_b32 v11, v11, 9, v56
	v_mul_f32_e32 v10, 0x3fb8aa3b, v10
	v_exp_f32_e32 v10, v10
	s_nop 0
	v_fma_mix_f32 v9, v9, v10, v13 op_sel_hi:[0,0,1]
	ds_read_b64 v[12:13], v11 offset:40960
	s_waitcnt lgkmcnt(0)
	v_cvt_f16_f32_e32 v11, v12
	v_cvt_f16_f32_e32 v15, v13
	v_cvt_pk_f16_f32 v16, v12, v13
	v_or_b32_e32 v12, s0, v6
	v_cvt_f32_f16_e32 v11, v11
	v_mov_b32_e32 v13, v7
	s_cselect_b32 s0, 6, 9
	v_lshlrev_b64 v[12:13], 10, v[12:13]
	v_mul_f32_e32 v11, 0x3fb8aa3b, v11
	v_exp_f32_e32 v22, v11
	v_or_b32_e32 v11, s0, v0
	v_lshl_add_u64 v[12:13], v[4:5], 0, v[12:13]
	v_lshl_or_b32 v11, v11, 9, v56
	global_store_dword v[12:13], v16, off nt
	ds_read_b64 v[12:13], v11 offset:40960
	v_fma_mix_f32 v9, v9, v22, v15 op_sel_hi:[0,0,1]
	s_waitcnt lgkmcnt(0)
	v_cvt_f16_f32_e32 v11, v12
	v_cvt_f16_f32_e32 v15, v13
	v_cvt_pk_f16_f32 v16, v12, v13
	v_or_b32_e32 v12, s0, v6
	v_cvt_f32_f16_e32 v11, v11
	v_mov_b32_e32 v13, v7
	v_lshlrev_b64 v[12:13], 10, v[12:13]
	v_lshl_add_u64 v[12:13], v[4:5], 0, v[12:13]
	v_mul_f32_e32 v11, 0x3fb8aa3b, v11
	s_cselect_b32 s0, 7, 8
	global_store_dword v[12:13], v16, off nt
	v_exp_f32_e32 v12, v11
	v_or_b32_e32 v11, s0, v0
	v_lshl_or_b32 v11, v11, 9, v56
	ds_read_b64 v[16:17], v11 offset:40960
	v_fma_mix_f32 v9, v9, v12, v15 op_sel_hi:[0,0,1]
	s_waitcnt lgkmcnt(0)
	v_cvt_f16_f32_e32 v11, v16
	v_cvt_f16_f32_e32 v13, v17
	v_cvt_pk_f16_f32 v15, v16, v17
	v_or_b32_e32 v16, s0, v6
	v_cvt_f32_f16_e32 v11, v11
	v_mov_b32_e32 v17, v7
	s_cselect_b32 s0, 8, 7
	v_lshlrev_b64 v[16:17], 10, v[16:17]
	v_mul_f32_e32 v11, 0x3fb8aa3b, v11
	v_exp_f32_e32 v18, v11
	v_or_b32_e32 v11, s0, v0
	v_lshl_add_u64 v[16:17], v[4:5], 0, v[16:17]
	v_lshl_or_b32 v11, v11, 9, v56
	global_store_dword v[16:17], v15, off nt
	ds_read_b64 v[16:17], v11 offset:40960
	v_fma_mix_f32 v9, v9, v18, v13 op_sel_hi:[0,0,1]
	s_waitcnt lgkmcnt(0)
	v_cvt_f16_f32_e32 v11, v16
	v_cvt_f16_f32_e32 v13, v17
	v_cvt_pk_f16_f32 v15, v16, v17
	v_or_b32_e32 v16, s0, v6
	v_cvt_f32_f16_e32 v11, v11
	v_mov_b32_e32 v17, v7
	v_lshlrev_b64 v[16:17], 10, v[16:17]
	v_lshl_add_u64 v[16:17], v[4:5], 0, v[16:17]
	v_mul_f32_e32 v11, 0x3fb8aa3b, v11
	global_store_dword v[16:17], v15, off nt
	v_exp_f32_e32 v16, v11
	s_cselect_b32 s0, 9, 6
	v_fma_mix_f32 v15, v9, v16, v13 op_sel_hi:[0,0,1]
	v_or_b32_e32 v9, s0, v0
	v_lshl_or_b32 v9, v9, 9, v56
	ds_read_b64 v[80:81], v9 offset:40960
	s_waitcnt lgkmcnt(0)
	v_cvt_f16_f32_e32 v11, v81
	v_cvt_f16_f32_e32 v9, v80
	v_cvt_pk_f16_f32 v13, v80, v81
	v_or_b32_e32 v80, s0, v6
	v_mov_b32_e32 v81, v7
	s_cselect_b32 s0, 10, 5
	v_lshlrev_b64 v[80:81], 10, v[80:81]
	v_cvt_f32_f16_e32 v21, v11
	v_or_b32_e32 v11, s0, v0
	v_lshl_add_u64 v[80:81], v[4:5], 0, v[80:81]
	v_lshl_or_b32 v11, v11, 9, v56
	global_store_dword v[80:81], v13, off nt
	ds_read_b64 v[80:81], v11 offset:40960
	v_cvt_f32_f16_e32 v9, v9
	s_waitcnt lgkmcnt(0)
	v_cvt_f16_f32_e32 v11, v80
	v_mul_f32_e32 v9, 0x3fb8aa3b, v9
	v_cvt_f16_f32_e32 v13, v81
	v_exp_f32_e32 v9, v9
	v_cvt_f32_f16_e32 v11, v11
	v_cvt_pk_f16_f32 v17, v80, v81
	v_or_b32_e32 v80, s0, v6
	v_mov_b32_e32 v81, v7
	v_mul_f32_e32 v11, 0x3fb8aa3b, v11
	v_exp_f32_e32 v11, v11
	v_lshlrev_b64 v[80:81], 10, v[80:81]
	v_cvt_f32_f16_e32 v23, v13
	v_lshl_add_u64 v[80:81], v[4:5], 0, v[80:81]
	v_mul_f32_e32 v13, v14, v8
	v_pk_fma_f32 v[14:15], v[14:15], v[8:9], v[20:21]
	s_cselect_b32 s0, 11, 4
	global_store_dword v[80:81], v17, off nt
	v_mul_f32_e32 v80, v13, v20
	v_mov_b32_e32 v81, v15
	v_or_b32_e32 v8, s0, v0
	v_pk_mul_f32 v[14:15], v[80:81], v[10:11]
	v_lshl_or_b32 v8, v8, 9, v56
	v_pk_mul_f32 v[20:21], v[14:15], v[22:23]
	v_pk_fma_f32 v[14:15], v[80:81], v[10:11], v[22:23]
	ds_read_b64 v[22:23], v8 offset:40960
	v_mov_b32_e32 v14, v20
	s_waitcnt lgkmcnt(0)
; DI void lru_tile(const Params& P, int l, int b, int tile, int g, char* smem, bool final, const LruK& K) {
;     ...
;     {
;       float A = 1.f, h = 0.f;
; #pragma unroll
;       for (int e = 0; e < 16; e++) {
;         const int ee = dir == 0 ? e : 15 - e;
;         const float2 lb = ab[(tq * 16 + ee) * 64 + ch];
;         fp16x2 hv; hv[0] = (__fp16)lb.x; hv[1] = (__fp16)lb.y;
;         lab[((size_t)dir * TA + rowbase + t0 + tq * 16 + ee) * 256 + gc] = __builtin_bit_cast(unsigned, hv);
;         const float a = __expf((float)hv[0]), bt = (float)hv[1];
;         h = a * h + bt; A *= a;
;       }
;       subst[tq * 64 + ch] = make_float2(A, h);
;     }
;     __syncthreads();
;     if (tq == 0) {
;       float A = 1.f, h = 0.f;
; #pragma unroll
;       for (int s2 = 0; s2 < 4; s2++) { float2 ss = subst[(dir == 0 ? s2 : 3 - s2) * 64 + ch]; h = ss.x * h + ss.y; A *= ss.x; }
;       P.lsum[((size_t)((b * 2 + dir) * 132 + tile)) * 256 + gc] = make_float2(A, h);
;     }
;     __syncthreads();
;   }
	v_cvt_f16_f32_e32 v8, v22
	v_cvt_f16_f32_e32 v10, v23
	v_cvt_pk_f16_f32 v13, v22, v23
	v_or_b32_e32 v22, s0, v6
	v_cvt_f32_f16_e32 v8, v8
	v_mov_b32_e32 v23, v7
	v_lshlrev_b64 v[22:23], 10, v[22:23]
	v_lshl_add_u64 v[22:23], v[4:5], 0, v[22:23]
	v_mul_f32_e32 v8, 0x3fb8aa3b, v8
	s_cselect_b32 s0, 12, 3
	global_store_dword v[22:23], v13, off nt
	v_exp_f32_e32 v13, v8
	v_or_b32_e32 v8, s0, v0
	v_lshl_or_b32 v8, v8, 9, v56
	ds_read_b64 v[22:23], v8 offset:40960
	v_cvt_f32_f16_e32 v19, v10
	v_pk_mul_f32 v[20:21], v[20:21], v[12:13]
	v_mov_b32_e32 v82, v13
	s_waitcnt lgkmcnt(0)
	v_cvt_f16_f32_e32 v8, v22
	v_cvt_f16_f32_e32 v10, v23
	v_cvt_pk_f16_f32 v17, v22, v23
	v_or_b32_e32 v22, s0, v6
	v_cvt_f32_f16_e32 v8, v8
	v_mov_b32_e32 v23, v7
	v_lshlrev_b64 v[22:23], 10, v[22:23]
	v_lshl_add_u64 v[22:23], v[4:5], 0, v[22:23]
	v_mul_f32_e32 v8, 0x3fb8aa3b, v8
	s_cselect_b32 s0, 13, 2
	global_store_dword v[22:23], v17, off nt
	v_exp_f32_e32 v17, v8
	v_or_b32_e32 v8, s0, v0
	v_lshl_or_b32 v8, v8, 9, v56
	ds_read_b64 v[80:81], v8 offset:40960
	v_cvt_f32_f16_e32 v23, v10
	v_pk_mul_f32 v[20:21], v[20:21], v[18:19]
	v_pk_fma_f32 v[14:15], v[14:15], v[12:13], v[18:19]
	s_waitcnt lgkmcnt(0)
	v_cvt_f16_f32_e32 v8, v80
	v_cvt_f16_f32_e32 v10, v81
	v_cvt_pk_f16_f32 v22, v80, v81
	v_or_b32_e32 v80, s0, v6
	v_cvt_f32_f16_e32 v8, v8
	v_mov_b32_e32 v81, v7
	v_lshlrev_b64 v[80:81], 10, v[80:81]
	v_lshl_add_u64 v[80:81], v[4:5], 0, v[80:81]
	v_mul_f32_e32 v8, 0x3fb8aa3b, v8
	s_cselect_b32 s0, 14, 1
	global_store_dword v[80:81], v22, off nt
	v_exp_f32_e32 v81, v8
	v_or_b32_e32 v8, s0, v0
	v_lshl_or_b32 v8, v8, 9, v56
	ds_read_b64 v[84:85], v8 offset:40960
	v_cvt_f32_f16_e32 v83, v10
	v_mov_b32_e32 v21, v15
	v_pk_mul_f32 v[14:15], v[20:21], v[16:17]
	v_mov_b32_e32 v80, v11
	s_waitcnt lgkmcnt(0)
	v_cvt_f16_f32_e32 v8, v84
	v_cvt_f16_f32_e32 v10, v85
	v_cvt_pk_f16_f32 v22, v84, v85
	v_or_b32_e32 v84, s0, v6
	v_cvt_f32_f16_e32 v8, v8
	v_mov_b32_e32 v85, v7
	v_lshlrev_b64 v[84:85], 10, v[84:85]
	v_lshl_add_u64 v[84:85], v[4:5], 0, v[84:85]
	v_mul_f32_e32 v8, 0x3fb8aa3b, v8
	s_cselect_b32 s0, 15, 0
	global_store_dword v[84:85], v22, off nt
	v_exp_f32_e32 v85, v8
	v_or_b32_e32 v8, s0, v0
	v_lshl_or_b32 v8, v8, 9, v56
	ds_read_b64 v[88:89], v8 offset:40960
	v_or_b32_e32 v6, s0, v6
	v_lshlrev_b64 v[6:7], 10, v[6:7]
	v_lshl_add_u64 v[6:7], v[4:5], 0, v[6:7]
	v_cvt_f32_f16_e32 v87, v10
	s_waitcnt lgkmcnt(0)
	v_cvt_f16_f32_e32 v8, v88
	v_cvt_pk_f16_f32 v22, v88, v89
	global_store_dword v[6:7], v22, off nt
	v_cvt_f16_f32_e32 v10, v89
	v_cvt_f32_f16_e32 v6, v8
	v_mov_b32_e32 v22, v9
	v_mov_b32_e32 v84, v17
	v_cvt_f32_f16_e32 v89, v10
	v_mul_f32_e32 v6, 0x3fb8aa3b, v6
	v_exp_f32_e32 v7, v6
	v_mov_b32_e32 v6, v9
	v_mov_b32_e32 v86, v81
	v_mov_b32_e32 v12, v85
	v_pk_mul_f32 v[8:9], v[14:15], v[6:7]
	v_pk_fma_f32 v[14:15], v[20:21], v[16:17], v[22:23]
	v_mov_b32_e32 v6, v11
	v_mov_b32_e32 v14, v8
	v_pk_mul_f32 v[8:9], v[8:9], v[6:7]
	v_mov_b32_e32 v6, v13
	v_pk_mul_f32 v[8:9], v[8:9], v[6:7]
	v_pk_fma_f32 v[10:11], v[14:15], v[80:81], v[82:83]
	v_mov_b32_e32 v6, v81
	v_mov_b32_e32 v9, v11
	v_pk_mul_f32 v[10:11], v[8:9], v[84:85]
	v_pk_fma_f32 v[8:9], v[8:9], v[84:85], v[86:87]
	v_pk_mul_f32 v[10:11], v[10:11], v[6:7]
	v_mov_b32_e32 v6, v85
	v_mov_b32_e32 v8, v10
	v_pk_mul_f32 v[10:11], v[10:11], v[12:13]
	v_mov_b32_e32 v12, v7
	v_mov_b32_e32 v88, v7
	v_pk_mul_f32 v[10:11], v[10:11], v[12:13]
	v_pk_fma_f32 v[6:7], v[8:9], v[6:7], v[88:89]
	s_nop 0
	v_mov_b32_e32 v11, v7
	ds_write_b64 v1, v[10:11]
	s_waitcnt lgkmcnt(0)
	s_barrier
	s_and_saveexec_b64 s[0:1], s[4:5]
	s_cbranch_execz .LBB0_400
	s_and_b64 s[6:7], s[2:3], exec
	s_cselect_b32 s6, 0, 0x600
	v_add_u32_e32 v6, s6, v1
	s_cselect_b32 s6, s43, 0x400
	v_add_u32_e32 v8, s6, v1
	s_cselect_b32 s6, 0x400, s43
	v_add_u32_e32 v10, s6, v1
	s_cselect_b32 s6, 0x600, 0
	ds_read_b64 v[6:7], v6
	ds_read_b64 v[8:9], v8
	v_add_u32_e32 v12, s6, v1
	ds_read_b64 v[10:11], v10
	ds_read_b64 v[12:13], v12
	s_or_b32 s6, s20, s11
	s_waitcnt lgkmcnt(3)
	v_fma_f32 v7, 0, v6, v7
	s_waitcnt lgkmcnt(2)
	v_fmac_f32_e32 v9, v7, v8
	v_mul_f32_e32 v6, v6, v8
	s_waitcnt lgkmcnt(1)
	v_fma_f32 v7, v9, v10, v11
	s_mulk_i32 s6, 0x84
	s_waitcnt lgkmcnt(0)
	v_mov_b32_e32 v11, v12
	s_add_i32 s6, s6, s9
	v_pk_mul_f32 v[14:15], v[6:7], v[10:11]
	v_lshl_or_b32 v148, s6, 8, v53
	v_pk_mul_f32 v[14:15], v[14:15], v[12:13]
	v_pk_fma_f32 v[6:7], v[6:7], v[10:11], v[12:13]
	v_lshl_add_u64 v[8:9], v[148:149], 3, s[70:71]
	v_mov_b32_e32 v15, v7
	global_store_dwordx2 v[8:9], v[14:15], off nt
	s_branch .LBB0_400
